# swiglu epilogue: lane-split prefetched row-scale loads, no per-row dependent load chain (4 up-GEMM phases)
# speedup vs baseline: 1.0215x; 1.0215x over previous
;     __host__ __device__ bool next(int i, Unit& u) const {
;         const long L = (long)i * G + c; if (L >= nwg) return false;
;         int wgid = (int)L; { const int q = nwg / NXCD, r = nwg % NXCD, xcd = wgid % NXCD, off = wgid / NXCD; wgid = (xcd < r ? xcd * (q + 1) : r * (q + 1) + (xcd - r) * q) + off; }
;         const int nig = WGM * nN, gid = wgid / nig, fm = gid * WGM, gsz = (nM - fm) < WGM ? (nM - fm) : WGM;
;         u.pm = fm + ((wgid % nig) % gsz); u.pn = (wgid % nig) / gsz; return true;
;     }
;     __device__ __forceinline__ void operator()(AccRef acc, const pg8::Unit& u, int wr, int wc, int fr, int fq) const {
;     ...
;                 const int row = row0 + ai * 128 + m * 16;
;                 const float rs = rs_from(ssp + (size_t)row * 16, 4, 1.0f / 1024.0f);
.LBB0_365:
	v_lshl_add_u32 v246, s60, 8, v146
	v_and_b32_e32 v247, 24, v148
	v_lshlrev_b32_e32 v247, 1, v247
	v_lshl_add_u32 v247, v246, 6, v247
	global_load_dwordx4 v[230:233], v247, s[46:47]
	global_load_dwordx4 v[234:237], v247, s[46:47] offset:1024
	global_load_dwordx4 v[238:241], v247, s[46:47] offset:2048
	global_load_dwordx4 v[242:245], v247, s[46:47] offset:3072
	s_add_i32 s33, s33, 1
	s_mul_i32 s0, s33, s38
	s_mul_hi_u32 s1, s33, s39
	s_add_i32 s1, s1, s0
	s_mul_i32 s0, s33, s39
	s_add_u32 s2, s0, s18
	s_addc_u32 s3, s1, s17
	v_cmp_gt_i64_e32 vcc, s[2:3], v[142:143]
	v_cmp_lt_i64_e64 s[0:1], s[2:3], v[140:141]
	s_cbranch_vccnz .LBB0_367
	s_ashr_i32 s3, s2, 31
	s_lshr_b32 s3, s3, 29
	s_add_i32 s3, s2, s3
	s_ashr_i32 s22, s3, 3
	s_and_b32 s3, s3, -8
	s_sub_i32 s2, s2, s3
	s_cmp_lt_i32 s2, 0
	s_cselect_b32 s3, s19, 0x160
	s_mul_i32 s2, s3, s2
	s_add_i32 s2, s2, s22
	s_mul_hi_i32 s3, s2, 0x2e8ba2e9
	s_lshr_b32 s22, s3, 31
	s_ashr_i32 s3, s3, 5
	s_add_i32 s3, s3, s22
	s_lshl_b32 s22, s3, 3
	s_sub_i32 s23, 0x80, s22
	s_min_i32 s23, s23, 8
	s_abs_i32 s58, s23
	v_cvt_f32_u32_e32 v0, s58
	s_sub_i32 s62, 0, s58
	s_mulk_i32 s3, 0xb0
	s_sub_i32 s2, s2, s3
	v_rcp_iflag_f32_e32 v0, v0
	s_abs_i32 s3, s2
	s_xor_b32 s59, s2, s23
	s_ashr_i32 s59, s59, 31
	v_mul_f32_e32 v0, 0x4f7ffffe, v0
	v_cvt_u32_f32_e32 v0, v0
	s_nop 0
	v_readfirstlane_b32 s63, v0
	s_mul_i32 s62, s62, s63
	s_mul_hi_u32 s62, s63, s62
	s_add_i32 s63, s63, s62
	s_mul_hi_u32 s62, s3, s63
	s_mul_i32 s63, s62, s58
	s_sub_i32 s3, s3, s63
	s_add_i32 s64, s62, 1
	s_sub_i32 s63, s3, s58
	s_cmp_ge_u32 s3, s58
	s_cselect_b32 s62, s64, s62
	s_cselect_b32 s3, s63, s3
	s_add_i32 s63, s62, 1
	s_cmp_ge_u32 s3, s58
	s_cselect_b32 s3, s63, s62
	s_xor_b32 s3, s3, s59
	s_sub_i32 s58, s3, s59
	s_mul_i32 s3, s58, s23
	s_sub_i32 s2, s2, s3
	s_add_i32 s59, s2, s22

;     __device__ __forceinline__ void operator()(const f32x4 (&acc)[2], int srow, int cgp, int kq) const { one(acc[0], srow, 2 * cgp, kq); one(acc[1], srow, 2 * cgp + 1, kq); }
; __device__ __forceinline__ float rs_from(const float* p, int n4, float inv_n) {
;     float s = 0.f;
;     for (int i = 0; i < n4; ++i) { const f32x4 v = *(const f32x4*)(p + 4 * i); s += (v[0] + v[1]) + (v[2] + v[3]); }
;     return rsqrtf(s * inv_n + EPS);
;     __device__ __forceinline__ void operator()(AccRef acc, const pg8::Unit& u, int wr, int wc, int fr, int fq) const {
;         const int row0 = u.pm * 256 + wr * 64 + fr, col0 = u.pn * 128 + wc * 32 + 8 * fq;
; #pragma unroll
;         for (int ai = 0; ai < 2; ++ai)
; #pragma unroll
;             for (int m = 0; m < 4; ++m) {
;                 const int row = row0 + ai * 128 + m * 16;
;                 const float rs = rs_from(ssp + (size_t)row * 16, 4, 1.0f / 1024.0f);
;                 f32x4 o[2];
; #pragma unroll
;                 for (int n = 0; n < 2; ++n)
; #pragma unroll
;                     for (int j = 0; j < 4; ++j) {
;                         const float g = acc[ai][0][m][n][j] * rs, up = acc[ai][1][m][n][j] * rs;
;                         o[n][j] = g * __builtin_amdgcn_rcpf(1.0f + __expf(-g)) * up;
;                     }
;                 *(u32x4*)(act + (size_t)row * FF + col0) = pack8(o[0], o[1]);
.LBB0_376:
	v_add_u32_e32 v249, 0x2000, v247
	global_load_dwordx4 v[154:157], v249, s[46:47]
	global_load_dwordx4 v[158:161], v249, s[46:47] offset:1024
	global_load_dwordx4 v[162:165], v249, s[46:47] offset:2048
	global_load_dwordx4 v[166:169], v249, s[46:47] offset:3072
	v_mbcnt_lo_u32_b32 v170, -1, 0
	v_mbcnt_hi_u32_b32 v170, -1, v170
	v_xor_b32_e32 v171, 16, v170
	v_xor_b32_e32 v172, 32, v170
	v_lshlrev_b32_e32 v171, 2, v171
	v_lshlrev_b32_e32 v172, 2, v172
	v_lshl_or_b32 v173, s61, 7, v148
	v_lshlrev_b32_e32 v173, 1, v173
	v_mad_u32_u24 v248, v246, s51, v173
	s_waitcnt vmcnt(12)
	v_add_f32_e32 v230, v230, v231
	v_add_f32_e32 v232, v232, v233
	v_add_f32_e32 v234, v234, v235
	v_add_f32_e32 v236, v236, v237
	v_add_f32_e32 v238, v238, v239
	v_add_f32_e32 v240, v240, v241
	v_add_f32_e32 v242, v242, v243
	v_add_f32_e32 v244, v244, v245
	v_add_f32_e32 v230, v230, v232
	v_add_f32_e32 v234, v234, v236
	v_add_f32_e32 v238, v238, v240
	v_add_f32_e32 v242, v242, v244
	ds_bpermute_b32 v231, v171, v230
	ds_bpermute_b32 v235, v171, v234
	ds_bpermute_b32 v239, v171, v238
	ds_bpermute_b32 v243, v171, v242
	s_waitcnt lgkmcnt(0)
	v_add_f32_e32 v230, v230, v231
	v_add_f32_e32 v234, v234, v235
	v_add_f32_e32 v238, v238, v239
	v_add_f32_e32 v242, v242, v243
	ds_bpermute_b32 v231, v172, v230
	ds_bpermute_b32 v235, v172, v234
	ds_bpermute_b32 v239, v172, v238
	ds_bpermute_b32 v243, v172, v242
	s_waitcnt lgkmcnt(0)
	v_add_f32_e32 v230, v230, v231
	v_add_f32_e32 v234, v234, v235
	v_add_f32_e32 v238, v238, v239
	v_add_f32_e32 v242, v242, v243
	v_fmamk_f32 v230, v230, 0x3a800000, v152
	v_fmamk_f32 v234, v234, 0x3a800000, v152
	v_fmamk_f32 v238, v238, 0x3a800000, v152
	v_fmamk_f32 v242, v242, 0x3a800000, v152
	v_rsq_f32_e32 v230, v230
	v_rsq_f32_e32 v234, v234
	v_rsq_f32_e32 v238, v238
	v_rsq_f32_e32 v242, v242
	s_nop 0
	v_pk_mul_f32 v[116:117], v[116:117], v[230:231] op_sel_hi:[1,0]
	v_pk_mul_f32 v[118:119], v[118:119], v[230:231] op_sel_hi:[1,0]
	v_pk_mul_f32 v[112:113], v[112:113], v[230:231] op_sel_hi:[1,0]
	v_pk_mul_f32 v[114:115], v[114:115], v[230:231] op_sel_hi:[1,0]
	v_pk_mul_f32 v[124:125], v[124:125], v[230:231] op_sel_hi:[1,0]
	v_pk_mul_f32 v[126:127], v[126:127], v[230:231] op_sel_hi:[1,0]
	v_pk_mul_f32 v[120:121], v[120:121], v[230:231] op_sel_hi:[1,0]
	v_pk_mul_f32 v[122:123], v[122:123], v[230:231] op_sel_hi:[1,0]
	v_mul_f32_e32 v176, 0xbfb8aa3b, v116
	v_mul_f32_e32 v177, 0xbfb8aa3b, v117
	v_mul_f32_e32 v178, 0xbfb8aa3b, v118
	v_mul_f32_e32 v179, 0xbfb8aa3b, v119
	v_mul_f32_e32 v180, 0xbfb8aa3b, v112
	v_mul_f32_e32 v181, 0xbfb8aa3b, v113
	v_mul_f32_e32 v182, 0xbfb8aa3b, v114
	v_mul_f32_e32 v183, 0xbfb8aa3b, v115
	v_exp_f32_e32 v176, v176
	v_exp_f32_e32 v177, v177
	v_exp_f32_e32 v178, v178
	v_exp_f32_e32 v179, v179
	v_exp_f32_e32 v180, v180
	v_exp_f32_e32 v181, v181
	v_exp_f32_e32 v182, v182
	v_exp_f32_e32 v183, v183
	v_add_f32_e32 v176, 1.0, v176
	v_add_f32_e32 v177, 1.0, v177
	v_add_f32_e32 v178, 1.0, v178
	v_add_f32_e32 v179, 1.0, v179
	v_add_f32_e32 v180, 1.0, v180
	v_add_f32_e32 v181, 1.0, v181
	v_add_f32_e32 v182, 1.0, v182
	v_add_f32_e32 v183, 1.0, v183
	v_rcp_f32_e32 v176, v176
	v_rcp_f32_e32 v177, v177
	v_rcp_f32_e32 v178, v178
	v_rcp_f32_e32 v179, v179
	v_rcp_f32_e32 v180, v180
	v_rcp_f32_e32 v181, v181
	v_rcp_f32_e32 v182, v182
	v_rcp_f32_e32 v183, v183
	v_mul_f32_e32 v176, v116, v176
	v_mul_f32_e32 v177, v117, v177
	v_mul_f32_e32 v178, v118, v178
	v_mul_f32_e32 v179, v119, v179
	v_mul_f32_e32 v180, v112, v180
	v_mul_f32_e32 v181, v113, v181
	v_mul_f32_e32 v182, v114, v182
	v_mul_f32_e32 v183, v115, v183
	v_mul_f32_e32 v176, v124, v176
	v_mul_f32_e32 v177, v125, v177
	v_mul_f32_e32 v178, v126, v178
	v_mul_f32_e32 v179, v127, v179
	v_mul_f32_e32 v180, v120, v180
	v_mul_f32_e32 v181, v121, v181
	v_mul_f32_e32 v182, v122, v182
	v_mul_f32_e32 v183, v123, v183
	v_cvt_pk_bf16_f32 v192, v176, v177
	v_cvt_pk_bf16_f32 v193, v178, v179
	v_cvt_pk_bf16_f32 v194, v180, v181
	v_cvt_pk_bf16_f32 v195, v182, v183
	v_mov_b32_e32 v200, v248
	global_store_dwordx4 v200, v[192:195], s[48:49]
	v_pk_mul_f32 v[100:101], v[100:101], v[234:235] op_sel_hi:[1,0]
	v_pk_mul_f32 v[102:103], v[102:103], v[234:235] op_sel_hi:[1,0]
	v_pk_mul_f32 v[96:97], v[96:97], v[234:235] op_sel_hi:[1,0]
	v_pk_mul_f32 v[98:99], v[98:99], v[234:235] op_sel_hi:[1,0]
	v_pk_mul_f32 v[108:109], v[108:109], v[234:235] op_sel_hi:[1,0]
	v_pk_mul_f32 v[110:111], v[110:111], v[234:235] op_sel_hi:[1,0]
	v_pk_mul_f32 v[104:105], v[104:105], v[234:235] op_sel_hi:[1,0]
	v_pk_mul_f32 v[106:107], v[106:107], v[234:235] op_sel_hi:[1,0]
	v_mul_f32_e32 v184, 0xbfb8aa3b, v100
	v_mul_f32_e32 v185, 0xbfb8aa3b, v101
	v_mul_f32_e32 v186, 0xbfb8aa3b, v102
	v_mul_f32_e32 v187, 0xbfb8aa3b, v103
	v_mul_f32_e32 v188, 0xbfb8aa3b, v96
	v_mul_f32_e32 v189, 0xbfb8aa3b, v97
	v_mul_f32_e32 v190, 0xbfb8aa3b, v98
	v_mul_f32_e32 v191, 0xbfb8aa3b, v99
	v_exp_f32_e32 v184, v184
	v_exp_f32_e32 v185, v185
	v_exp_f32_e32 v186, v186
	v_exp_f32_e32 v187, v187
	v_exp_f32_e32 v188, v188
	v_exp_f32_e32 v189, v189
	v_exp_f32_e32 v190, v190
	v_exp_f32_e32 v191, v191
	v_add_f32_e32 v184, 1.0, v184
	v_add_f32_e32 v185, 1.0, v185
	v_add_f32_e32 v186, 1.0, v186
	v_add_f32_e32 v187, 1.0, v187
	v_add_f32_e32 v188, 1.0, v188
	v_add_f32_e32 v189, 1.0, v189
	v_add_f32_e32 v190, 1.0, v190
	v_add_f32_e32 v191, 1.0, v191
	v_rcp_f32_e32 v184, v184
	v_rcp_f32_e32 v185, v185
	v_rcp_f32_e32 v186, v186
	v_rcp_f32_e32 v187, v187
	v_rcp_f32_e32 v188, v188
	v_rcp_f32_e32 v189, v189
	v_rcp_f32_e32 v190, v190
	v_rcp_f32_e32 v191, v191
	v_mul_f32_e32 v184, v100, v184
	v_mul_f32_e32 v185, v101, v185
	v_mul_f32_e32 v186, v102, v186
	v_mul_f32_e32 v187, v103, v187
;     __device__ __forceinline__ void operator()(AccRef acc, const pg8::Unit& u, int wr, int wc, int fr, int fq) const {
;     ...
;         for (int ai = 0; ai < 2; ++ai)
; #pragma unroll
;             for (int m = 0; m < 4; ++m) {
;                 const int row = row0 + ai * 128 + m * 16;
;                 const float rs = rs_from(ssp + (size_t)row * 16, 4, 1.0f / 1024.0f);
;                 f32x4 o[2];
; #pragma unroll
;                 for (int n = 0; n < 2; ++n)
; #pragma unroll
;                     for (int j = 0; j < 4; ++j) {
;                         const float g = acc[ai][0][m][n][j] * rs, up = acc[ai][1][m][n][j] * rs;
;                         o[n][j] = g * __builtin_amdgcn_rcpf(1.0f + __expf(-g)) * up;
;                     }
;                 *(u32x4*)(act + (size_t)row * FF + col0) = pack8(o[0], o[1]);
	v_mul_f32_e32 v188, v96, v188
	v_mul_f32_e32 v189, v97, v189
	v_mul_f32_e32 v190, v98, v190
	v_mul_f32_e32 v191, v99, v191
	v_mul_f32_e32 v184, v108, v184
	v_mul_f32_e32 v185, v109, v185
	v_mul_f32_e32 v186, v110, v186
	v_mul_f32_e32 v187, v111, v187
	v_mul_f32_e32 v188, v104, v188
	v_mul_f32_e32 v189, v105, v189
	v_mul_f32_e32 v190, v106, v190
	v_mul_f32_e32 v191, v107, v191
	v_cvt_pk_bf16_f32 v196, v184, v185
	v_cvt_pk_bf16_f32 v197, v186, v187
	v_cvt_pk_bf16_f32 v198, v188, v189
	v_cvt_pk_bf16_f32 v199, v190, v191
	v_add_u32_e32 v201, 0x16000, v248
	global_store_dwordx4 v201, v[196:199], s[48:49]
	v_pk_mul_f32 v[84:85], v[84:85], v[238:239] op_sel_hi:[1,0]
	v_pk_mul_f32 v[86:87], v[86:87], v[238:239] op_sel_hi:[1,0]
	v_pk_mul_f32 v[80:81], v[80:81], v[238:239] op_sel_hi:[1,0]
	v_pk_mul_f32 v[82:83], v[82:83], v[238:239] op_sel_hi:[1,0]
	v_pk_mul_f32 v[92:93], v[92:93], v[238:239] op_sel_hi:[1,0]
	v_pk_mul_f32 v[94:95], v[94:95], v[238:239] op_sel_hi:[1,0]
	v_pk_mul_f32 v[88:89], v[88:89], v[238:239] op_sel_hi:[1,0]
	v_pk_mul_f32 v[90:91], v[90:91], v[238:239] op_sel_hi:[1,0]
	v_mul_f32_e32 v176, 0xbfb8aa3b, v84
	v_mul_f32_e32 v177, 0xbfb8aa3b, v85
	v_mul_f32_e32 v178, 0xbfb8aa3b, v86
	v_mul_f32_e32 v179, 0xbfb8aa3b, v87
	v_mul_f32_e32 v180, 0xbfb8aa3b, v80
	v_mul_f32_e32 v181, 0xbfb8aa3b, v81
	v_mul_f32_e32 v182, 0xbfb8aa3b, v82
	v_mul_f32_e32 v183, 0xbfb8aa3b, v83
	v_exp_f32_e32 v176, v176
	v_exp_f32_e32 v177, v177
	v_exp_f32_e32 v178, v178
	v_exp_f32_e32 v179, v179
	v_exp_f32_e32 v180, v180
	v_exp_f32_e32 v181, v181
	v_exp_f32_e32 v182, v182
	v_exp_f32_e32 v183, v183
	v_add_f32_e32 v176, 1.0, v176
	v_add_f32_e32 v177, 1.0, v177
	v_add_f32_e32 v178, 1.0, v178
	v_add_f32_e32 v179, 1.0, v179
	v_add_f32_e32 v180, 1.0, v180
	v_add_f32_e32 v181, 1.0, v181
	v_add_f32_e32 v182, 1.0, v182
	v_add_f32_e32 v183, 1.0, v183
	v_rcp_f32_e32 v176, v176
	v_rcp_f32_e32 v177, v177
	v_rcp_f32_e32 v178, v178
	v_rcp_f32_e32 v179, v179
	v_rcp_f32_e32 v180, v180
	v_rcp_f32_e32 v181, v181
	v_rcp_f32_e32 v182, v182
	v_rcp_f32_e32 v183, v183
	v_mul_f32_e32 v176, v84, v176
	v_mul_f32_e32 v177, v85, v177
	v_mul_f32_e32 v178, v86, v178
	v_mul_f32_e32 v179, v87, v179
	v_mul_f32_e32 v180, v80, v180
	v_mul_f32_e32 v181, v81, v181
	v_mul_f32_e32 v182, v82, v182
	v_mul_f32_e32 v183, v83, v183
	v_mul_f32_e32 v176, v92, v176
	v_mul_f32_e32 v177, v93, v177
	v_mul_f32_e32 v178, v94, v178
	v_mul_f32_e32 v179, v95, v179
	v_mul_f32_e32 v180, v88, v180
	v_mul_f32_e32 v181, v89, v181
	v_mul_f32_e32 v182, v90, v182
	v_mul_f32_e32 v183, v91, v183
	v_cvt_pk_bf16_f32 v192, v176, v177
	v_cvt_pk_bf16_f32 v193, v178, v179
	v_cvt_pk_bf16_f32 v194, v180, v181
	v_cvt_pk_bf16_f32 v195, v182, v183
	v_add_u32_e32 v200, 0x2c000, v248
	global_store_dwordx4 v200, v[192:195], s[48:49]
	v_pk_mul_f32 v[68:69], v[68:69], v[242:243] op_sel_hi:[1,0]
	v_pk_mul_f32 v[70:71], v[70:71], v[242:243] op_sel_hi:[1,0]
	v_pk_mul_f32 v[64:65], v[64:65], v[242:243] op_sel_hi:[1,0]
	v_pk_mul_f32 v[66:67], v[66:67], v[242:243] op_sel_hi:[1,0]
	v_pk_mul_f32 v[76:77], v[76:77], v[242:243] op_sel_hi:[1,0]
	v_pk_mul_f32 v[78:79], v[78:79], v[242:243] op_sel_hi:[1,0]
	v_pk_mul_f32 v[72:73], v[72:73], v[242:243] op_sel_hi:[1,0]
	v_pk_mul_f32 v[74:75], v[74:75], v[242:243] op_sel_hi:[1,0]
	v_mul_f32_e32 v184, 0xbfb8aa3b, v68
	v_mul_f32_e32 v185, 0xbfb8aa3b, v69
	v_mul_f32_e32 v186, 0xbfb8aa3b, v70
	v_mul_f32_e32 v187, 0xbfb8aa3b, v71
	v_mul_f32_e32 v188, 0xbfb8aa3b, v64
	v_mul_f32_e32 v189, 0xbfb8aa3b, v65
	v_mul_f32_e32 v190, 0xbfb8aa3b, v66
	v_mul_f32_e32 v191, 0xbfb8aa3b, v67
	v_exp_f32_e32 v184, v184
	v_exp_f32_e32 v185, v185
	v_exp_f32_e32 v186, v186
	v_exp_f32_e32 v187, v187
	v_exp_f32_e32 v188, v188
	v_exp_f32_e32 v189, v189
	v_exp_f32_e32 v190, v190
	v_exp_f32_e32 v191, v191
	v_add_f32_e32 v184, 1.0, v184
	v_add_f32_e32 v185, 1.0, v185
	v_add_f32_e32 v186, 1.0, v186
	v_add_f32_e32 v187, 1.0, v187
	v_add_f32_e32 v188, 1.0, v188
	v_add_f32_e32 v189, 1.0, v189
	v_add_f32_e32 v190, 1.0, v190
	v_add_f32_e32 v191, 1.0, v191
	v_rcp_f32_e32 v184, v184
	v_rcp_f32_e32 v185, v185
	v_rcp_f32_e32 v186, v186
	v_rcp_f32_e32 v187, v187
	v_rcp_f32_e32 v188, v188
	v_rcp_f32_e32 v189, v189
	v_rcp_f32_e32 v190, v190
	v_rcp_f32_e32 v191, v191
	v_mul_f32_e32 v184, v68, v184
	v_mul_f32_e32 v185, v69, v185
	v_mul_f32_e32 v186, v70, v186
	v_mul_f32_e32 v187, v71, v187
	v_mul_f32_e32 v188, v64, v188
	v_mul_f32_e32 v189, v65, v189
	v_mul_f32_e32 v190, v66, v190
	v_mul_f32_e32 v191, v67, v191
	v_mul_f32_e32 v184, v76, v184
	v_mul_f32_e32 v185, v77, v185
	v_mul_f32_e32 v186, v78, v186
	v_mul_f32_e32 v187, v79, v187
	v_mul_f32_e32 v188, v72, v188
	v_mul_f32_e32 v189, v73, v189
	v_mul_f32_e32 v190, v74, v190
	v_mul_f32_e32 v191, v75, v191
	v_cvt_pk_bf16_f32 v196, v184, v185
	v_cvt_pk_bf16_f32 v197, v186, v187
	v_cvt_pk_bf16_f32 v198, v188, v189
	v_cvt_pk_bf16_f32 v199, v190, v191
	v_add_u32_e32 v201, 0x42000, v248
	global_store_dwordx4 v201, v[196:199], s[48:49]
	s_waitcnt vmcnt(4)
	v_add_f32_e32 v154, v154, v155
	v_add_f32_e32 v156, v156, v157
	v_add_f32_e32 v158, v158, v159
	v_add_f32_e32 v160, v160, v161
	v_add_f32_e32 v162, v162, v163
	v_add_f32_e32 v164, v164, v165
	v_add_f32_e32 v166, v166, v167
	v_add_f32_e32 v168, v168, v169
	v_add_f32_e32 v154, v154, v156
	v_add_f32_e32 v158, v158, v160
	v_add_f32_e32 v162, v162, v164
	v_add_f32_e32 v166, v166, v168
	ds_bpermute_b32 v155, v171, v154
	ds_bpermute_b32 v159, v171, v158
	ds_bpermute_b32 v163, v171, v162
	ds_bpermute_b32 v167, v171, v166
	s_waitcnt lgkmcnt(0)
; __device__ __forceinline__ float rs_from(const float* p, int n4, float inv_n) {
;     float s = 0.f;
;     for (int i = 0; i < n4; ++i) { const f32x4 v = *(const f32x4*)(p + 4 * i); s += (v[0] + v[1]) + (v[2] + v[3]); }
;     return rsqrtf(s * inv_n + EPS);
;     __device__ __forceinline__ void operator()(AccRef acc, const pg8::Unit& u, int wr, int wc, int fr, int fq) const {
;     ...
;         for (int ai = 0; ai < 2; ++ai)
; #pragma unroll
;             for (int m = 0; m < 4; ++m) {
;                 const int row = row0 + ai * 128 + m * 16;
;                 const float rs = rs_from(ssp + (size_t)row * 16, 4, 1.0f / 1024.0f);
;                 f32x4 o[2];
; #pragma unroll
;                 for (int n = 0; n < 2; ++n)
; #pragma unroll
;                     for (int j = 0; j < 4; ++j) {
;                         const float g = acc[ai][0][m][n][j] * rs, up = acc[ai][1][m][n][j] * rs;
;                         o[n][j] = g * __builtin_amdgcn_rcpf(1.0f + __expf(-g)) * up;
;                     }
;                 *(u32x4*)(act + (size_t)row * FF + col0) = pack8(o[0], o[1]);
	v_add_f32_e32 v154, v154, v155
	v_add_f32_e32 v158, v158, v159
	v_add_f32_e32 v162, v162, v163
	v_add_f32_e32 v166, v166, v167
	ds_bpermute_b32 v155, v172, v154
	ds_bpermute_b32 v159, v172, v158
	ds_bpermute_b32 v163, v172, v162
	ds_bpermute_b32 v167, v172, v166
	s_waitcnt lgkmcnt(0)
	v_add_f32_e32 v154, v154, v155
	v_add_f32_e32 v158, v158, v159
	v_add_f32_e32 v162, v162, v163
	v_add_f32_e32 v166, v166, v167
	v_fmamk_f32 v154, v154, 0x3a800000, v152
	v_fmamk_f32 v158, v158, 0x3a800000, v152
	v_fmamk_f32 v162, v162, 0x3a800000, v152
	v_fmamk_f32 v166, v166, 0x3a800000, v152
	v_rsq_f32_e32 v154, v154
	v_rsq_f32_e32 v158, v158
	v_rsq_f32_e32 v162, v162
	v_rsq_f32_e32 v166, v166
	s_nop 0
	v_pk_mul_f32 v[52:53], v[52:53], v[154:155] op_sel_hi:[1,0]
	v_pk_mul_f32 v[54:55], v[54:55], v[154:155] op_sel_hi:[1,0]
	v_pk_mul_f32 v[48:49], v[48:49], v[154:155] op_sel_hi:[1,0]
	v_pk_mul_f32 v[50:51], v[50:51], v[154:155] op_sel_hi:[1,0]
	v_pk_mul_f32 v[60:61], v[60:61], v[154:155] op_sel_hi:[1,0]
	v_pk_mul_f32 v[62:63], v[62:63], v[154:155] op_sel_hi:[1,0]
	v_pk_mul_f32 v[56:57], v[56:57], v[154:155] op_sel_hi:[1,0]
	v_pk_mul_f32 v[58:59], v[58:59], v[154:155] op_sel_hi:[1,0]
	v_mul_f32_e32 v176, 0xbfb8aa3b, v52
	v_mul_f32_e32 v177, 0xbfb8aa3b, v53
	v_mul_f32_e32 v178, 0xbfb8aa3b, v54
	v_mul_f32_e32 v179, 0xbfb8aa3b, v55
	v_mul_f32_e32 v180, 0xbfb8aa3b, v48
	v_mul_f32_e32 v181, 0xbfb8aa3b, v49
	v_mul_f32_e32 v182, 0xbfb8aa3b, v50
	v_mul_f32_e32 v183, 0xbfb8aa3b, v51
	v_exp_f32_e32 v176, v176
	v_exp_f32_e32 v177, v177
	v_exp_f32_e32 v178, v178
	v_exp_f32_e32 v179, v179
	v_exp_f32_e32 v180, v180
	v_exp_f32_e32 v181, v181
	v_exp_f32_e32 v182, v182
	v_exp_f32_e32 v183, v183
	v_add_f32_e32 v176, 1.0, v176
	v_add_f32_e32 v177, 1.0, v177
	v_add_f32_e32 v178, 1.0, v178
	v_add_f32_e32 v179, 1.0, v179
	v_add_f32_e32 v180, 1.0, v180
	v_add_f32_e32 v181, 1.0, v181
	v_add_f32_e32 v182, 1.0, v182
	v_add_f32_e32 v183, 1.0, v183
	v_rcp_f32_e32 v176, v176
	v_rcp_f32_e32 v177, v177
	v_rcp_f32_e32 v178, v178
	v_rcp_f32_e32 v179, v179
	v_rcp_f32_e32 v180, v180
	v_rcp_f32_e32 v181, v181
	v_rcp_f32_e32 v182, v182
	v_rcp_f32_e32 v183, v183
	v_mul_f32_e32 v176, v52, v176
	v_mul_f32_e32 v177, v53, v177
	v_mul_f32_e32 v178, v54, v178
	v_mul_f32_e32 v179, v55, v179
	v_mul_f32_e32 v180, v48, v180
	v_mul_f32_e32 v181, v49, v181
	v_mul_f32_e32 v182, v50, v182
	v_mul_f32_e32 v183, v51, v183
	v_mul_f32_e32 v176, v60, v176
	v_mul_f32_e32 v177, v61, v177
	v_mul_f32_e32 v178, v62, v178
	v_mul_f32_e32 v179, v63, v179
	v_mul_f32_e32 v180, v56, v180
	v_mul_f32_e32 v181, v57, v181
	v_mul_f32_e32 v182, v58, v182
	v_mul_f32_e32 v183, v59, v183
	v_cvt_pk_bf16_f32 v192, v176, v177
	v_cvt_pk_bf16_f32 v193, v178, v179
	v_cvt_pk_bf16_f32 v194, v180, v181
	v_cvt_pk_bf16_f32 v195, v182, v183
	v_add_u32_e32 v200, 0xb0000, v248
	global_store_dwordx4 v200, v[192:195], s[48:49]
	v_pk_mul_f32 v[36:37], v[36:37], v[158:159] op_sel_hi:[1,0]
	v_pk_mul_f32 v[38:39], v[38:39], v[158:159] op_sel_hi:[1,0]
	v_pk_mul_f32 v[32:33], v[32:33], v[158:159] op_sel_hi:[1,0]
	v_pk_mul_f32 v[34:35], v[34:35], v[158:159] op_sel_hi:[1,0]
	v_pk_mul_f32 v[44:45], v[44:45], v[158:159] op_sel_hi:[1,0]
	v_pk_mul_f32 v[46:47], v[46:47], v[158:159] op_sel_hi:[1,0]
	v_pk_mul_f32 v[40:41], v[40:41], v[158:159] op_sel_hi:[1,0]
	v_pk_mul_f32 v[42:43], v[42:43], v[158:159] op_sel_hi:[1,0]
	v_mul_f32_e32 v184, 0xbfb8aa3b, v36
	v_mul_f32_e32 v185, 0xbfb8aa3b, v37
	v_mul_f32_e32 v186, 0xbfb8aa3b, v38
	v_mul_f32_e32 v187, 0xbfb8aa3b, v39
	v_mul_f32_e32 v188, 0xbfb8aa3b, v32
	v_mul_f32_e32 v189, 0xbfb8aa3b, v33
	v_mul_f32_e32 v190, 0xbfb8aa3b, v34
	v_mul_f32_e32 v191, 0xbfb8aa3b, v35
	v_exp_f32_e32 v184, v184
	v_exp_f32_e32 v185, v185
	v_exp_f32_e32 v186, v186
	v_exp_f32_e32 v187, v187
	v_exp_f32_e32 v188, v188
	v_exp_f32_e32 v189, v189
	v_exp_f32_e32 v190, v190
	v_exp_f32_e32 v191, v191
	v_add_f32_e32 v184, 1.0, v184
	v_add_f32_e32 v185, 1.0, v185
	v_add_f32_e32 v186, 1.0, v186
	v_add_f32_e32 v187, 1.0, v187
	v_add_f32_e32 v188, 1.0, v188
	v_add_f32_e32 v189, 1.0, v189
	v_add_f32_e32 v190, 1.0, v190
	v_add_f32_e32 v191, 1.0, v191
	v_rcp_f32_e32 v184, v184
	v_rcp_f32_e32 v185, v185
	v_rcp_f32_e32 v186, v186
	v_rcp_f32_e32 v187, v187
	v_rcp_f32_e32 v188, v188
	v_rcp_f32_e32 v189, v189
	v_rcp_f32_e32 v190, v190
	v_rcp_f32_e32 v191, v191
	v_mul_f32_e32 v184, v36, v184
	v_mul_f32_e32 v185, v37, v185
	v_mul_f32_e32 v186, v38, v186
	v_mul_f32_e32 v187, v39, v187
	v_mul_f32_e32 v188, v32, v188
	v_mul_f32_e32 v189, v33, v189
	v_mul_f32_e32 v190, v34, v190
	v_mul_f32_e32 v191, v35, v191
	v_mul_f32_e32 v184, v44, v184
	v_mul_f32_e32 v185, v45, v185
	v_mul_f32_e32 v186, v46, v186
	v_mul_f32_e32 v187, v47, v187
	v_mul_f32_e32 v188, v40, v188
	v_mul_f32_e32 v189, v41, v189
; #define PG8_WAIT_V(n) asm volatile("s_waitcnt vmcnt(" #n ")" ::: "memory")
; template <class Epi, class Sched, bool ALIGN_EPI = false, bool SP2 = false>
; __device__ __forceinline__ void gemm_phase(PG8_LAS unsigned char* lds, const Gemm g, const Sched& S, const Epi& E) {
;     ...
;         for (int t = 0; t < nt; t += 2) {
;             const bool last = (t == nt - 2);
;             const char* a1 = cA + (size_t)(t + 1) * kstep;
;             const char* a2 = last ? nA : cA + (size_t)(t + 2) * kstep; const char* b2 = last ? nB : cB + (size_t)(t + 2) * kstep;
;             const char* a3 = a2 + kstep; const char* b3 = b2 + kstep;
;             if (last && has_next) S.a_ready(nxt);
;             if constexpr (SP2) {
;             PG8_LDB(B0, 0, 0); PG8_LDB(B1, 0, 1); PG8_SCHED; PG8_LDA(At, 0, 0); PG8_STAGE(PG8_SA(1, 1), a1 + hstep, voffA);
;             PG8_WAIT_V(8); PG8_WAIT_L(0); PG8_BAR; PG8_MMA(0, 0, At, B0); PG8_MMA(0, 1, At, B1); PG8_BAR; PG8_SCHED;
;             PG8_LDA(At, 0, 1); PG8_STAGE(PG8_SB(0, 0), b2, voffB); PG8_STAGE(PG8_SB(0, 1), b2 + hstep, voffB); PG8_STAGE(PG8_SA(0, 0), a2, voffA);
;             PG8_WAIT_V(8); PG8_WAIT_L(0); PG8_BAR; PG8_MMA(1, 0, At, B0); PG8_MMA(1, 1, At, B1); PG8_BAR; PG8_SCHED;
;             PG8_LDB(B0, 1, 0); PG8_LDB(B1, 1, 1); PG8_SCHED; PG8_LDA(At, 1, 0); PG8_STAGE(PG8_SA(0, 1), a2 + hstep, voffA);
;             PG8_WAIT_V(8); PG8_WAIT_L(0); PG8_BAR; PG8_MMA(0, 0, At, B0); PG8_MMA(0, 1, At, B1); PG8_BAR; PG8_SCHED;
;             PG8_LDA(At, 1, 1); PG8_STAGE(PG8_SB(1, 0), b3, voffB); PG8_STAGE(PG8_SB(1, 1), b3 + hstep, voffB); PG8_STAGE(PG8_SA(1, 0), a3, voffA);
;     __device__ __forceinline__ void operator()(AccRef acc, const pg8::Unit& u, int wr, int wc, int fr, int fq) const {
;     ...
;             for (int m = 0; m < 4; ++m) {
;                 const int row = row0 + ai * 128 + m * 16;
;                 const float rs = rs_from(ssp + (size_t)row * 16, 4, 1.0f / 1024.0f);
;                 f32x4 o[2];
; #pragma unroll
;                 for (int n = 0; n < 2; ++n)
; #pragma unroll
;                     for (int j = 0; j < 4; ++j) {
;                         const float g = acc[ai][0][m][n][j] * rs, up = acc[ai][1][m][n][j] * rs;
;                         o[n][j] = g * __builtin_amdgcn_rcpf(1.0f + __expf(-g)) * up;
;                     }
;                 *(u32x4*)(act + (size_t)row * FF + col0) = pack8(o[0], o[1]);
	v_mul_f32_e32 v190, v42, v190
	v_mul_f32_e32 v191, v43, v191
	v_cvt_pk_bf16_f32 v196, v184, v185
	v_cvt_pk_bf16_f32 v197, v186, v187
	v_cvt_pk_bf16_f32 v198, v188, v189
	v_cvt_pk_bf16_f32 v199, v190, v191
	v_add_u32_e32 v201, 0xc6000, v248
	global_store_dwordx4 v201, v[196:199], s[48:49]
	v_pk_mul_f32 v[20:21], v[20:21], v[162:163] op_sel_hi:[1,0]
	v_pk_mul_f32 v[22:23], v[22:23], v[162:163] op_sel_hi:[1,0]
	v_pk_mul_f32 v[16:17], v[16:17], v[162:163] op_sel_hi:[1,0]
	v_pk_mul_f32 v[18:19], v[18:19], v[162:163] op_sel_hi:[1,0]
	v_pk_mul_f32 v[28:29], v[28:29], v[162:163] op_sel_hi:[1,0]
	v_pk_mul_f32 v[30:31], v[30:31], v[162:163] op_sel_hi:[1,0]
	v_pk_mul_f32 v[24:25], v[24:25], v[162:163] op_sel_hi:[1,0]
	v_pk_mul_f32 v[26:27], v[26:27], v[162:163] op_sel_hi:[1,0]
	v_mul_f32_e32 v176, 0xbfb8aa3b, v20
	v_mul_f32_e32 v177, 0xbfb8aa3b, v21
	v_mul_f32_e32 v178, 0xbfb8aa3b, v22
	v_mul_f32_e32 v179, 0xbfb8aa3b, v23
	v_mul_f32_e32 v180, 0xbfb8aa3b, v16
	v_mul_f32_e32 v181, 0xbfb8aa3b, v17
	v_mul_f32_e32 v182, 0xbfb8aa3b, v18
	v_mul_f32_e32 v183, 0xbfb8aa3b, v19
	v_exp_f32_e32 v176, v176
	v_exp_f32_e32 v177, v177
	v_exp_f32_e32 v178, v178
	v_exp_f32_e32 v179, v179
	v_exp_f32_e32 v180, v180
	v_exp_f32_e32 v181, v181
	v_exp_f32_e32 v182, v182
	v_exp_f32_e32 v183, v183
	v_add_f32_e32 v176, 1.0, v176
	v_add_f32_e32 v177, 1.0, v177
	v_add_f32_e32 v178, 1.0, v178
	v_add_f32_e32 v179, 1.0, v179
	v_add_f32_e32 v180, 1.0, v180
	v_add_f32_e32 v181, 1.0, v181
	v_add_f32_e32 v182, 1.0, v182
	v_add_f32_e32 v183, 1.0, v183
	v_rcp_f32_e32 v176, v176
	v_rcp_f32_e32 v177, v177
	v_rcp_f32_e32 v178, v178
	v_rcp_f32_e32 v179, v179
	v_rcp_f32_e32 v180, v180
	v_rcp_f32_e32 v181, v181
	v_rcp_f32_e32 v182, v182
	v_rcp_f32_e32 v183, v183
	v_mul_f32_e32 v176, v20, v176
	v_mul_f32_e32 v177, v21, v177
	v_mul_f32_e32 v178, v22, v178
	v_mul_f32_e32 v179, v23, v179
	v_mul_f32_e32 v180, v16, v180
	v_mul_f32_e32 v181, v17, v181
	v_mul_f32_e32 v182, v18, v182
	v_mul_f32_e32 v183, v19, v183
	v_mul_f32_e32 v176, v28, v176
	v_mul_f32_e32 v177, v29, v177
	v_mul_f32_e32 v178, v30, v178
	v_mul_f32_e32 v179, v31, v179
	v_mul_f32_e32 v180, v24, v180
	v_mul_f32_e32 v181, v25, v181
	v_mul_f32_e32 v182, v26, v182
	v_mul_f32_e32 v183, v27, v183
	v_cvt_pk_bf16_f32 v192, v176, v177
	v_cvt_pk_bf16_f32 v193, v178, v179
	v_cvt_pk_bf16_f32 v194, v180, v181
	v_cvt_pk_bf16_f32 v195, v182, v183
	v_add_u32_e32 v200, 0xdc000, v248
	global_store_dwordx4 v200, v[192:195], s[48:49]
	v_pk_mul_f32 v[4:5], v[4:5], v[166:167] op_sel_hi:[1,0]
	v_pk_mul_f32 v[6:7], v[6:7], v[166:167] op_sel_hi:[1,0]
	v_pk_mul_f32 v[0:1], v[0:1], v[166:167] op_sel_hi:[1,0]
	v_pk_mul_f32 v[2:3], v[2:3], v[166:167] op_sel_hi:[1,0]
	v_pk_mul_f32 v[12:13], v[12:13], v[166:167] op_sel_hi:[1,0]
	v_pk_mul_f32 v[14:15], v[14:15], v[166:167] op_sel_hi:[1,0]
	v_pk_mul_f32 v[8:9], v[8:9], v[166:167] op_sel_hi:[1,0]
	v_pk_mul_f32 v[10:11], v[10:11], v[166:167] op_sel_hi:[1,0]
	v_mul_f32_e32 v184, 0xbfb8aa3b, v4
	v_mul_f32_e32 v185, 0xbfb8aa3b, v5
	v_mul_f32_e32 v186, 0xbfb8aa3b, v6
	v_mul_f32_e32 v187, 0xbfb8aa3b, v7
	v_mul_f32_e32 v188, 0xbfb8aa3b, v0
	v_mul_f32_e32 v189, 0xbfb8aa3b, v1
	v_mul_f32_e32 v190, 0xbfb8aa3b, v2
	v_mul_f32_e32 v191, 0xbfb8aa3b, v3
	v_exp_f32_e32 v184, v184
	v_exp_f32_e32 v185, v185
	v_exp_f32_e32 v186, v186
	v_exp_f32_e32 v187, v187
	v_exp_f32_e32 v188, v188
	v_exp_f32_e32 v189, v189
	v_exp_f32_e32 v190, v190
	v_exp_f32_e32 v191, v191
	v_add_f32_e32 v184, 1.0, v184
	v_add_f32_e32 v185, 1.0, v185
	v_add_f32_e32 v186, 1.0, v186
	v_add_f32_e32 v187, 1.0, v187
	v_add_f32_e32 v188, 1.0, v188
	v_add_f32_e32 v189, 1.0, v189
	v_add_f32_e32 v190, 1.0, v190
	v_add_f32_e32 v191, 1.0, v191
	v_rcp_f32_e32 v184, v184
	v_rcp_f32_e32 v185, v185
	v_rcp_f32_e32 v186, v186
	v_rcp_f32_e32 v187, v187
	v_rcp_f32_e32 v188, v188
	v_rcp_f32_e32 v189, v189
	v_rcp_f32_e32 v190, v190
	v_rcp_f32_e32 v191, v191
	v_mul_f32_e32 v184, v4, v184
	v_mul_f32_e32 v185, v5, v185
	v_mul_f32_e32 v186, v6, v186
	v_mul_f32_e32 v187, v7, v187
	v_mul_f32_e32 v188, v0, v188
	v_mul_f32_e32 v189, v1, v189
	v_mul_f32_e32 v190, v2, v190
	v_mul_f32_e32 v191, v3, v191
	v_mul_f32_e32 v184, v12, v184
	v_mul_f32_e32 v185, v13, v185
	v_mul_f32_e32 v186, v14, v186
	v_mul_f32_e32 v187, v15, v187
	v_mul_f32_e32 v188, v8, v188
	v_mul_f32_e32 v189, v9, v189
	v_mul_f32_e32 v190, v10, v190
	v_mul_f32_e32 v191, v11, v191
	v_cvt_pk_bf16_f32 v196, v184, v185
	v_cvt_pk_bf16_f32 v197, v186, v187
	v_cvt_pk_bf16_f32 v198, v188, v189
	v_cvt_pk_bf16_f32 v199, v190, v191
	v_add_u32_e32 v201, 0xf2000, v248
	global_store_dwordx4 v201, v[196:199], s[48:49]
	s_and_b64 vcc, exec, s[2:3]
	s_mov_b64 s[2:3], -1
	s_cbranch_vccnz .LBB0_364
	s_andn2_b64 vcc, exec, s[10:11]
	s_cbranch_vccnz .LBB0_363
	s_barrier
	s_branch .LBB0_363

;     __host__ __device__ bool next(int i, Unit& u) const {
;         const long L = (long)i * G + c; if (L >= nwg) return false;
;         int wgid = (int)L; { const int q = nwg / NXCD, r = nwg % NXCD, xcd = wgid % NXCD, off = wgid / NXCD; wgid = (xcd < r ? xcd * (q + 1) : r * (q + 1) + (xcd - r) * q) + off; }
;         const int nig = WGM * nN, gid = wgid / nig, fm = gid * WGM, gsz = (nM - fm) < WGM ? (nM - fm) : WGM;
;         u.pm = fm + ((wgid % nig) % gsz); u.pn = (wgid % nig) / gsz; return true;
;     }
;     __device__ __forceinline__ void operator()(AccRef acc, const pg8::Unit& u, int wr, int wc, int fr, int fq) const {
;     ...
;                 const int row = row0 + ai * 128 + m * 16;
;                 const float rs = rs_from(ssp + (size_t)row * 16, 4, 1.0f / 1024.0f);
.LBB0_1309:
	v_lshl_add_u32 v246, s60, 8, v146
	v_and_b32_e32 v247, 24, v148
	v_lshlrev_b32_e32 v247, 1, v247
	v_lshl_add_u32 v247, v246, 6, v247
	global_load_dwordx4 v[230:233], v247, s[46:47]
	global_load_dwordx4 v[234:237], v247, s[46:47] offset:1024
	global_load_dwordx4 v[238:241], v247, s[46:47] offset:2048
	global_load_dwordx4 v[242:245], v247, s[46:47] offset:3072
	s_add_i32 s35, s35, 1
	s_mul_i32 s0, s35, s40
	s_mul_hi_u32 s1, s35, s41
	s_add_i32 s1, s1, s0
	s_mul_i32 s0, s35, s41
	s_add_u32 s2, s0, s18
	s_addc_u32 s3, s1, s17
	v_cmp_gt_i64_e32 vcc, s[2:3], v[142:143]
	v_cmp_lt_i64_e64 s[0:1], s[2:3], v[140:141]
	s_cbranch_vccnz .LBB0_1311
	s_ashr_i32 s3, s2, 31
	s_lshr_b32 s3, s3, 29
	s_add_i32 s3, s2, s3
	s_ashr_i32 s24, s3, 3
	s_and_b32 s3, s3, -8
	s_sub_i32 s2, s2, s3
	s_cmp_lt_i32 s2, 0
	s_cselect_b32 s3, s19, 0x160
	s_mul_i32 s2, s3, s2
	s_add_i32 s2, s2, s24
	s_mul_hi_i32 s3, s2, 0x2e8ba2e9
	s_lshr_b32 s24, s3, 31
	s_ashr_i32 s3, s3, 5
	s_add_i32 s3, s3, s24
	s_lshl_b32 s24, s3, 3
	s_sub_i32 s25, 0x80, s24
	s_min_i32 s25, s25, 8
	s_abs_i32 s58, s25
	v_cvt_f32_u32_e32 v0, s58
	s_sub_i32 s62, 0, s58
	s_mulk_i32 s3, 0xb0
	s_sub_i32 s2, s2, s3
	v_rcp_iflag_f32_e32 v0, v0
	s_abs_i32 s3, s2
	s_xor_b32 s59, s2, s25
	s_ashr_i32 s59, s59, 31
	v_mul_f32_e32 v0, 0x4f7ffffe, v0
	v_cvt_u32_f32_e32 v0, v0
	s_nop 0
	v_readfirstlane_b32 s63, v0
	s_mul_i32 s62, s62, s63
	s_mul_hi_u32 s62, s63, s62
	s_add_i32 s63, s63, s62
	s_mul_hi_u32 s62, s3, s63
	s_mul_i32 s63, s62, s58
	s_sub_i32 s3, s3, s63
	s_add_i32 s64, s62, 1
	s_sub_i32 s63, s3, s58
	s_cmp_ge_u32 s3, s58
	s_cselect_b32 s62, s64, s62
	s_cselect_b32 s3, s63, s3
	s_add_i32 s63, s62, 1
	s_cmp_ge_u32 s3, s58
	s_cselect_b32 s3, s63, s62
	s_xor_b32 s3, s3, s59
	s_sub_i32 s58, s3, s59
	s_mul_i32 s3, s58, s25
	s_sub_i32 s2, s2, s3
	s_add_i32 s59, s2, s24

;     __device__ __forceinline__ void operator()(const f32x4 (&acc)[2], int srow, int cgp, int kq) const { one(acc[0], srow, 2 * cgp, kq); one(acc[1], srow, 2 * cgp + 1, kq); }
; __device__ __forceinline__ float rs_from(const float* p, int n4, float inv_n) {
;     float s = 0.f;
;     for (int i = 0; i < n4; ++i) { const f32x4 v = *(const f32x4*)(p + 4 * i); s += (v[0] + v[1]) + (v[2] + v[3]); }
;     return rsqrtf(s * inv_n + EPS);
;     __device__ __forceinline__ void operator()(AccRef acc, const pg8::Unit& u, int wr, int wc, int fr, int fq) const {
;         const int row0 = u.pm * 256 + wr * 64 + fr, col0 = u.pn * 128 + wc * 32 + 8 * fq;
; #pragma unroll
;         for (int ai = 0; ai < 2; ++ai)
; #pragma unroll
;             for (int m = 0; m < 4; ++m) {
;                 const int row = row0 + ai * 128 + m * 16;
;                 const float rs = rs_from(ssp + (size_t)row * 16, 4, 1.0f / 1024.0f);
;                 f32x4 o[2];
; #pragma unroll
;                 for (int n = 0; n < 2; ++n)
; #pragma unroll
;                     for (int j = 0; j < 4; ++j) {
;                         const float g = acc[ai][0][m][n][j] * rs, up = acc[ai][1][m][n][j] * rs;
;                         o[n][j] = g * __builtin_amdgcn_rcpf(1.0f + __expf(-g)) * up;
;                     }
;                 *(u32x4*)(act + (size_t)row * FF + col0) = pack8(o[0], o[1]);
.LBB0_1320:
	v_add_u32_e32 v249, 0x2000, v247
	global_load_dwordx4 v[154:157], v249, s[46:47]
	global_load_dwordx4 v[158:161], v249, s[46:47] offset:1024
	global_load_dwordx4 v[162:165], v249, s[46:47] offset:2048
	global_load_dwordx4 v[166:169], v249, s[46:47] offset:3072
	v_mbcnt_lo_u32_b32 v170, -1, 0
	v_mbcnt_hi_u32_b32 v170, -1, v170
	v_xor_b32_e32 v171, 16, v170
	v_xor_b32_e32 v172, 32, v170
	v_lshlrev_b32_e32 v171, 2, v171
	v_lshlrev_b32_e32 v172, 2, v172
	v_lshl_or_b32 v173, s61, 7, v148
	v_lshlrev_b32_e32 v173, 1, v173
	v_mad_u32_u24 v248, v246, s57, v173
	s_waitcnt vmcnt(12)
	v_add_f32_e32 v230, v230, v231
	v_add_f32_e32 v232, v232, v233
	v_add_f32_e32 v234, v234, v235
	v_add_f32_e32 v236, v236, v237
	v_add_f32_e32 v238, v238, v239
	v_add_f32_e32 v240, v240, v241
	v_add_f32_e32 v242, v242, v243
	v_add_f32_e32 v244, v244, v245
	v_add_f32_e32 v230, v230, v232
	v_add_f32_e32 v234, v234, v236
	v_add_f32_e32 v238, v238, v240
	v_add_f32_e32 v242, v242, v244
	ds_bpermute_b32 v231, v171, v230
	ds_bpermute_b32 v235, v171, v234
	ds_bpermute_b32 v239, v171, v238
	ds_bpermute_b32 v243, v171, v242
	s_waitcnt lgkmcnt(0)
	v_add_f32_e32 v230, v230, v231
	v_add_f32_e32 v234, v234, v235
	v_add_f32_e32 v238, v238, v239
	v_add_f32_e32 v242, v242, v243
	ds_bpermute_b32 v231, v172, v230
	ds_bpermute_b32 v235, v172, v234
	ds_bpermute_b32 v239, v172, v238
	ds_bpermute_b32 v243, v172, v242
	s_waitcnt lgkmcnt(0)
	v_add_f32_e32 v230, v230, v231
	v_add_f32_e32 v234, v234, v235
	v_add_f32_e32 v238, v238, v239
	v_add_f32_e32 v242, v242, v243
	v_fmamk_f32 v230, v230, 0x3a800000, v152
	v_fmamk_f32 v234, v234, 0x3a800000, v152
	v_fmamk_f32 v238, v238, 0x3a800000, v152
	v_fmamk_f32 v242, v242, 0x3a800000, v152
	v_rsq_f32_e32 v230, v230
	v_rsq_f32_e32 v234, v234
	v_rsq_f32_e32 v238, v238
	v_rsq_f32_e32 v242, v242
	s_nop 0
	v_pk_mul_f32 v[116:117], v[116:117], v[230:231] op_sel_hi:[1,0]
	v_pk_mul_f32 v[118:119], v[118:119], v[230:231] op_sel_hi:[1,0]
	v_pk_mul_f32 v[112:113], v[112:113], v[230:231] op_sel_hi:[1,0]
	v_pk_mul_f32 v[114:115], v[114:115], v[230:231] op_sel_hi:[1,0]
	v_pk_mul_f32 v[124:125], v[124:125], v[230:231] op_sel_hi:[1,0]
	v_pk_mul_f32 v[126:127], v[126:127], v[230:231] op_sel_hi:[1,0]
	v_pk_mul_f32 v[120:121], v[120:121], v[230:231] op_sel_hi:[1,0]
	v_pk_mul_f32 v[122:123], v[122:123], v[230:231] op_sel_hi:[1,0]
	v_mul_f32_e32 v176, 0xbfb8aa3b, v116
	v_mul_f32_e32 v177, 0xbfb8aa3b, v117
	v_mul_f32_e32 v178, 0xbfb8aa3b, v118
	v_mul_f32_e32 v179, 0xbfb8aa3b, v119
	v_mul_f32_e32 v180, 0xbfb8aa3b, v112
	v_mul_f32_e32 v181, 0xbfb8aa3b, v113
	v_mul_f32_e32 v182, 0xbfb8aa3b, v114
	v_mul_f32_e32 v183, 0xbfb8aa3b, v115
	v_exp_f32_e32 v176, v176
	v_exp_f32_e32 v177, v177
	v_exp_f32_e32 v178, v178
	v_exp_f32_e32 v179, v179
	v_exp_f32_e32 v180, v180
	v_exp_f32_e32 v181, v181
	v_exp_f32_e32 v182, v182
	v_exp_f32_e32 v183, v183
	v_add_f32_e32 v176, 1.0, v176
	v_add_f32_e32 v177, 1.0, v177
	v_add_f32_e32 v178, 1.0, v178
	v_add_f32_e32 v179, 1.0, v179
	v_add_f32_e32 v180, 1.0, v180
	v_add_f32_e32 v181, 1.0, v181
	v_add_f32_e32 v182, 1.0, v182
	v_add_f32_e32 v183, 1.0, v183
	v_rcp_f32_e32 v176, v176
	v_rcp_f32_e32 v177, v177
	v_rcp_f32_e32 v178, v178
	v_rcp_f32_e32 v179, v179
	v_rcp_f32_e32 v180, v180
	v_rcp_f32_e32 v181, v181
	v_rcp_f32_e32 v182, v182
	v_rcp_f32_e32 v183, v183
	v_mul_f32_e32 v176, v116, v176
	v_mul_f32_e32 v177, v117, v177
	v_mul_f32_e32 v178, v118, v178
	v_mul_f32_e32 v179, v119, v179
	v_mul_f32_e32 v180, v112, v180
	v_mul_f32_e32 v181, v113, v181
	v_mul_f32_e32 v182, v114, v182
	v_mul_f32_e32 v183, v115, v183
	v_mul_f32_e32 v176, v124, v176
	v_mul_f32_e32 v177, v125, v177
	v_mul_f32_e32 v178, v126, v178
	v_mul_f32_e32 v179, v127, v179
	v_mul_f32_e32 v180, v120, v180
	v_mul_f32_e32 v181, v121, v181
	v_mul_f32_e32 v182, v122, v182
	v_mul_f32_e32 v183, v123, v183
	v_cvt_pk_bf16_f32 v192, v176, v177
	v_cvt_pk_bf16_f32 v193, v178, v179
	v_cvt_pk_bf16_f32 v194, v180, v181
	v_cvt_pk_bf16_f32 v195, v182, v183
	v_mov_b32_e32 v200, v248
	global_store_dwordx4 v200, v[192:195], s[48:49]
	v_pk_mul_f32 v[100:101], v[100:101], v[234:235] op_sel_hi:[1,0]
	v_pk_mul_f32 v[102:103], v[102:103], v[234:235] op_sel_hi:[1,0]
	v_pk_mul_f32 v[96:97], v[96:97], v[234:235] op_sel_hi:[1,0]
	v_pk_mul_f32 v[98:99], v[98:99], v[234:235] op_sel_hi:[1,0]
	v_pk_mul_f32 v[108:109], v[108:109], v[234:235] op_sel_hi:[1,0]
	v_pk_mul_f32 v[110:111], v[110:111], v[234:235] op_sel_hi:[1,0]
	v_pk_mul_f32 v[104:105], v[104:105], v[234:235] op_sel_hi:[1,0]
	v_pk_mul_f32 v[106:107], v[106:107], v[234:235] op_sel_hi:[1,0]
	v_mul_f32_e32 v184, 0xbfb8aa3b, v100
	v_mul_f32_e32 v185, 0xbfb8aa3b, v101
	v_mul_f32_e32 v186, 0xbfb8aa3b, v102
	v_mul_f32_e32 v187, 0xbfb8aa3b, v103
	v_mul_f32_e32 v188, 0xbfb8aa3b, v96
	v_mul_f32_e32 v189, 0xbfb8aa3b, v97
	v_mul_f32_e32 v190, 0xbfb8aa3b, v98
	v_mul_f32_e32 v191, 0xbfb8aa3b, v99
	v_exp_f32_e32 v184, v184
	v_exp_f32_e32 v185, v185
	v_exp_f32_e32 v186, v186
	v_exp_f32_e32 v187, v187
	v_exp_f32_e32 v188, v188
	v_exp_f32_e32 v189, v189
	v_exp_f32_e32 v190, v190
	v_exp_f32_e32 v191, v191
	v_add_f32_e32 v184, 1.0, v184
	v_add_f32_e32 v185, 1.0, v185
	v_add_f32_e32 v186, 1.0, v186
	v_add_f32_e32 v187, 1.0, v187
	v_add_f32_e32 v188, 1.0, v188
	v_add_f32_e32 v189, 1.0, v189
	v_add_f32_e32 v190, 1.0, v190
	v_add_f32_e32 v191, 1.0, v191
	v_rcp_f32_e32 v184, v184
	v_rcp_f32_e32 v185, v185
	v_rcp_f32_e32 v186, v186
	v_rcp_f32_e32 v187, v187
	v_rcp_f32_e32 v188, v188
	v_rcp_f32_e32 v189, v189
	v_rcp_f32_e32 v190, v190
	v_rcp_f32_e32 v191, v191
	v_mul_f32_e32 v184, v100, v184
	v_mul_f32_e32 v185, v101, v185
	v_mul_f32_e32 v186, v102, v186
	v_mul_f32_e32 v187, v103, v187
;     __device__ __forceinline__ void operator()(AccRef acc, const pg8::Unit& u, int wr, int wc, int fr, int fq) const {
;     ...
;         for (int ai = 0; ai < 2; ++ai)
; #pragma unroll
;             for (int m = 0; m < 4; ++m) {
;                 const int row = row0 + ai * 128 + m * 16;
;                 const float rs = rs_from(ssp + (size_t)row * 16, 4, 1.0f / 1024.0f);
;                 f32x4 o[2];
; #pragma unroll
;                 for (int n = 0; n < 2; ++n)
; #pragma unroll
;                     for (int j = 0; j < 4; ++j) {
;                         const float g = acc[ai][0][m][n][j] * rs, up = acc[ai][1][m][n][j] * rs;
;                         o[n][j] = g * __builtin_amdgcn_rcpf(1.0f + __expf(-g)) * up;
;                     }
;                 *(u32x4*)(act + (size_t)row * FF + col0) = pack8(o[0], o[1]);
	v_mul_f32_e32 v188, v96, v188
	v_mul_f32_e32 v189, v97, v189
	v_mul_f32_e32 v190, v98, v190
	v_mul_f32_e32 v191, v99, v191
	v_mul_f32_e32 v184, v108, v184
	v_mul_f32_e32 v185, v109, v185
	v_mul_f32_e32 v186, v110, v186
	v_mul_f32_e32 v187, v111, v187
	v_mul_f32_e32 v188, v104, v188
	v_mul_f32_e32 v189, v105, v189
	v_mul_f32_e32 v190, v106, v190
	v_mul_f32_e32 v191, v107, v191
	v_cvt_pk_bf16_f32 v196, v184, v185
	v_cvt_pk_bf16_f32 v197, v186, v187
	v_cvt_pk_bf16_f32 v198, v188, v189
	v_cvt_pk_bf16_f32 v199, v190, v191
	v_add_u32_e32 v201, 0x16000, v248
	global_store_dwordx4 v201, v[196:199], s[48:49]
	v_pk_mul_f32 v[84:85], v[84:85], v[238:239] op_sel_hi:[1,0]
	v_pk_mul_f32 v[86:87], v[86:87], v[238:239] op_sel_hi:[1,0]
	v_pk_mul_f32 v[80:81], v[80:81], v[238:239] op_sel_hi:[1,0]
	v_pk_mul_f32 v[82:83], v[82:83], v[238:239] op_sel_hi:[1,0]
	v_pk_mul_f32 v[92:93], v[92:93], v[238:239] op_sel_hi:[1,0]
	v_pk_mul_f32 v[94:95], v[94:95], v[238:239] op_sel_hi:[1,0]
	v_pk_mul_f32 v[88:89], v[88:89], v[238:239] op_sel_hi:[1,0]
	v_pk_mul_f32 v[90:91], v[90:91], v[238:239] op_sel_hi:[1,0]
	v_mul_f32_e32 v176, 0xbfb8aa3b, v84
	v_mul_f32_e32 v177, 0xbfb8aa3b, v85
	v_mul_f32_e32 v178, 0xbfb8aa3b, v86
	v_mul_f32_e32 v179, 0xbfb8aa3b, v87
	v_mul_f32_e32 v180, 0xbfb8aa3b, v80
	v_mul_f32_e32 v181, 0xbfb8aa3b, v81
	v_mul_f32_e32 v182, 0xbfb8aa3b, v82
	v_mul_f32_e32 v183, 0xbfb8aa3b, v83
	v_exp_f32_e32 v176, v176
	v_exp_f32_e32 v177, v177
	v_exp_f32_e32 v178, v178
	v_exp_f32_e32 v179, v179
	v_exp_f32_e32 v180, v180
	v_exp_f32_e32 v181, v181
	v_exp_f32_e32 v182, v182
	v_exp_f32_e32 v183, v183
	v_add_f32_e32 v176, 1.0, v176
	v_add_f32_e32 v177, 1.0, v177
	v_add_f32_e32 v178, 1.0, v178
	v_add_f32_e32 v179, 1.0, v179
	v_add_f32_e32 v180, 1.0, v180
	v_add_f32_e32 v181, 1.0, v181
	v_add_f32_e32 v182, 1.0, v182
	v_add_f32_e32 v183, 1.0, v183
	v_rcp_f32_e32 v176, v176
	v_rcp_f32_e32 v177, v177
	v_rcp_f32_e32 v178, v178
	v_rcp_f32_e32 v179, v179
	v_rcp_f32_e32 v180, v180
	v_rcp_f32_e32 v181, v181
	v_rcp_f32_e32 v182, v182
	v_rcp_f32_e32 v183, v183
	v_mul_f32_e32 v176, v84, v176
	v_mul_f32_e32 v177, v85, v177
	v_mul_f32_e32 v178, v86, v178
	v_mul_f32_e32 v179, v87, v179
	v_mul_f32_e32 v180, v80, v180
	v_mul_f32_e32 v181, v81, v181
	v_mul_f32_e32 v182, v82, v182
	v_mul_f32_e32 v183, v83, v183
	v_mul_f32_e32 v176, v92, v176
	v_mul_f32_e32 v177, v93, v177
	v_mul_f32_e32 v178, v94, v178
	v_mul_f32_e32 v179, v95, v179
	v_mul_f32_e32 v180, v88, v180
	v_mul_f32_e32 v181, v89, v181
	v_mul_f32_e32 v182, v90, v182
	v_mul_f32_e32 v183, v91, v183
	v_cvt_pk_bf16_f32 v192, v176, v177
	v_cvt_pk_bf16_f32 v193, v178, v179
	v_cvt_pk_bf16_f32 v194, v180, v181
	v_cvt_pk_bf16_f32 v195, v182, v183
	v_add_u32_e32 v200, 0x2c000, v248
	global_store_dwordx4 v200, v[192:195], s[48:49]
	v_pk_mul_f32 v[68:69], v[68:69], v[242:243] op_sel_hi:[1,0]
	v_pk_mul_f32 v[70:71], v[70:71], v[242:243] op_sel_hi:[1,0]
	v_pk_mul_f32 v[64:65], v[64:65], v[242:243] op_sel_hi:[1,0]
	v_pk_mul_f32 v[66:67], v[66:67], v[242:243] op_sel_hi:[1,0]
	v_pk_mul_f32 v[76:77], v[76:77], v[242:243] op_sel_hi:[1,0]
	v_pk_mul_f32 v[78:79], v[78:79], v[242:243] op_sel_hi:[1,0]
	v_pk_mul_f32 v[72:73], v[72:73], v[242:243] op_sel_hi:[1,0]
	v_pk_mul_f32 v[74:75], v[74:75], v[242:243] op_sel_hi:[1,0]
	v_mul_f32_e32 v184, 0xbfb8aa3b, v68
	v_mul_f32_e32 v185, 0xbfb8aa3b, v69
	v_mul_f32_e32 v186, 0xbfb8aa3b, v70
	v_mul_f32_e32 v187, 0xbfb8aa3b, v71
	v_mul_f32_e32 v188, 0xbfb8aa3b, v64
	v_mul_f32_e32 v189, 0xbfb8aa3b, v65
	v_mul_f32_e32 v190, 0xbfb8aa3b, v66
	v_mul_f32_e32 v191, 0xbfb8aa3b, v67
	v_exp_f32_e32 v184, v184
	v_exp_f32_e32 v185, v185
	v_exp_f32_e32 v186, v186
	v_exp_f32_e32 v187, v187
	v_exp_f32_e32 v188, v188
	v_exp_f32_e32 v189, v189
	v_exp_f32_e32 v190, v190
	v_exp_f32_e32 v191, v191
	v_add_f32_e32 v184, 1.0, v184
	v_add_f32_e32 v185, 1.0, v185
	v_add_f32_e32 v186, 1.0, v186
	v_add_f32_e32 v187, 1.0, v187
	v_add_f32_e32 v188, 1.0, v188
	v_add_f32_e32 v189, 1.0, v189
	v_add_f32_e32 v190, 1.0, v190
	v_add_f32_e32 v191, 1.0, v191
	v_rcp_f32_e32 v184, v184
	v_rcp_f32_e32 v185, v185
	v_rcp_f32_e32 v186, v186
	v_rcp_f32_e32 v187, v187
	v_rcp_f32_e32 v188, v188
	v_rcp_f32_e32 v189, v189
	v_rcp_f32_e32 v190, v190
	v_rcp_f32_e32 v191, v191
	v_mul_f32_e32 v184, v68, v184
	v_mul_f32_e32 v185, v69, v185
	v_mul_f32_e32 v186, v70, v186
	v_mul_f32_e32 v187, v71, v187
	v_mul_f32_e32 v188, v64, v188
	v_mul_f32_e32 v189, v65, v189
	v_mul_f32_e32 v190, v66, v190
	v_mul_f32_e32 v191, v67, v191
	v_mul_f32_e32 v184, v76, v184
	v_mul_f32_e32 v185, v77, v185
	v_mul_f32_e32 v186, v78, v186
	v_mul_f32_e32 v187, v79, v187
	v_mul_f32_e32 v188, v72, v188
	v_mul_f32_e32 v189, v73, v189
	v_mul_f32_e32 v190, v74, v190
	v_mul_f32_e32 v191, v75, v191
	v_cvt_pk_bf16_f32 v196, v184, v185
	v_cvt_pk_bf16_f32 v197, v186, v187
	v_cvt_pk_bf16_f32 v198, v188, v189
	v_cvt_pk_bf16_f32 v199, v190, v191
	v_add_u32_e32 v201, 0x42000, v248
	global_store_dwordx4 v201, v[196:199], s[48:49]
	s_waitcnt vmcnt(4)
	v_add_f32_e32 v154, v154, v155
	v_add_f32_e32 v156, v156, v157
	v_add_f32_e32 v158, v158, v159
	v_add_f32_e32 v160, v160, v161
	v_add_f32_e32 v162, v162, v163
	v_add_f32_e32 v164, v164, v165
	v_add_f32_e32 v166, v166, v167
	v_add_f32_e32 v168, v168, v169
	v_add_f32_e32 v154, v154, v156
	v_add_f32_e32 v158, v158, v160
	v_add_f32_e32 v162, v162, v164
	v_add_f32_e32 v166, v166, v168
	ds_bpermute_b32 v155, v171, v154
	ds_bpermute_b32 v159, v171, v158
	ds_bpermute_b32 v163, v171, v162
	ds_bpermute_b32 v167, v171, v166
	s_waitcnt lgkmcnt(0)
; __device__ __forceinline__ float rs_from(const float* p, int n4, float inv_n) {
;     float s = 0.f;
;     for (int i = 0; i < n4; ++i) { const f32x4 v = *(const f32x4*)(p + 4 * i); s += (v[0] + v[1]) + (v[2] + v[3]); }
;     return rsqrtf(s * inv_n + EPS);
;     __device__ __forceinline__ void operator()(AccRef acc, const pg8::Unit& u, int wr, int wc, int fr, int fq) const {
;     ...
;         for (int ai = 0; ai < 2; ++ai)
; #pragma unroll
;             for (int m = 0; m < 4; ++m) {
;                 const int row = row0 + ai * 128 + m * 16;
;                 const float rs = rs_from(ssp + (size_t)row * 16, 4, 1.0f / 1024.0f);
;                 f32x4 o[2];
; #pragma unroll
;                 for (int n = 0; n < 2; ++n)
; #pragma unroll
;                     for (int j = 0; j < 4; ++j) {
;                         const float g = acc[ai][0][m][n][j] * rs, up = acc[ai][1][m][n][j] * rs;
;                         o[n][j] = g * __builtin_amdgcn_rcpf(1.0f + __expf(-g)) * up;
;                     }
;                 *(u32x4*)(act + (size_t)row * FF + col0) = pack8(o[0], o[1]);
	v_add_f32_e32 v154, v154, v155
	v_add_f32_e32 v158, v158, v159
	v_add_f32_e32 v162, v162, v163
	v_add_f32_e32 v166, v166, v167
	ds_bpermute_b32 v155, v172, v154
	ds_bpermute_b32 v159, v172, v158
	ds_bpermute_b32 v163, v172, v162
	ds_bpermute_b32 v167, v172, v166
	s_waitcnt lgkmcnt(0)
	v_add_f32_e32 v154, v154, v155
	v_add_f32_e32 v158, v158, v159
	v_add_f32_e32 v162, v162, v163
	v_add_f32_e32 v166, v166, v167
	v_fmamk_f32 v154, v154, 0x3a800000, v152
	v_fmamk_f32 v158, v158, 0x3a800000, v152
	v_fmamk_f32 v162, v162, 0x3a800000, v152
	v_fmamk_f32 v166, v166, 0x3a800000, v152
	v_rsq_f32_e32 v154, v154
	v_rsq_f32_e32 v158, v158
	v_rsq_f32_e32 v162, v162
	v_rsq_f32_e32 v166, v166
	s_nop 0
	v_pk_mul_f32 v[52:53], v[52:53], v[154:155] op_sel_hi:[1,0]
	v_pk_mul_f32 v[54:55], v[54:55], v[154:155] op_sel_hi:[1,0]
	v_pk_mul_f32 v[48:49], v[48:49], v[154:155] op_sel_hi:[1,0]
	v_pk_mul_f32 v[50:51], v[50:51], v[154:155] op_sel_hi:[1,0]
	v_pk_mul_f32 v[60:61], v[60:61], v[154:155] op_sel_hi:[1,0]
	v_pk_mul_f32 v[62:63], v[62:63], v[154:155] op_sel_hi:[1,0]
	v_pk_mul_f32 v[56:57], v[56:57], v[154:155] op_sel_hi:[1,0]
	v_pk_mul_f32 v[58:59], v[58:59], v[154:155] op_sel_hi:[1,0]
	v_mul_f32_e32 v176, 0xbfb8aa3b, v52
	v_mul_f32_e32 v177, 0xbfb8aa3b, v53
	v_mul_f32_e32 v178, 0xbfb8aa3b, v54
	v_mul_f32_e32 v179, 0xbfb8aa3b, v55
	v_mul_f32_e32 v180, 0xbfb8aa3b, v48
	v_mul_f32_e32 v181, 0xbfb8aa3b, v49
	v_mul_f32_e32 v182, 0xbfb8aa3b, v50
	v_mul_f32_e32 v183, 0xbfb8aa3b, v51
	v_exp_f32_e32 v176, v176
	v_exp_f32_e32 v177, v177
	v_exp_f32_e32 v178, v178
	v_exp_f32_e32 v179, v179
	v_exp_f32_e32 v180, v180
	v_exp_f32_e32 v181, v181
	v_exp_f32_e32 v182, v182
	v_exp_f32_e32 v183, v183
	v_add_f32_e32 v176, 1.0, v176
	v_add_f32_e32 v177, 1.0, v177
	v_add_f32_e32 v178, 1.0, v178
	v_add_f32_e32 v179, 1.0, v179
	v_add_f32_e32 v180, 1.0, v180
	v_add_f32_e32 v181, 1.0, v181
	v_add_f32_e32 v182, 1.0, v182
	v_add_f32_e32 v183, 1.0, v183
	v_rcp_f32_e32 v176, v176
	v_rcp_f32_e32 v177, v177
	v_rcp_f32_e32 v178, v178
	v_rcp_f32_e32 v179, v179
	v_rcp_f32_e32 v180, v180
	v_rcp_f32_e32 v181, v181
	v_rcp_f32_e32 v182, v182
	v_rcp_f32_e32 v183, v183
	v_mul_f32_e32 v176, v52, v176
	v_mul_f32_e32 v177, v53, v177
	v_mul_f32_e32 v178, v54, v178
	v_mul_f32_e32 v179, v55, v179
	v_mul_f32_e32 v180, v48, v180
	v_mul_f32_e32 v181, v49, v181
	v_mul_f32_e32 v182, v50, v182
	v_mul_f32_e32 v183, v51, v183
	v_mul_f32_e32 v176, v60, v176
	v_mul_f32_e32 v177, v61, v177
	v_mul_f32_e32 v178, v62, v178
	v_mul_f32_e32 v179, v63, v179
	v_mul_f32_e32 v180, v56, v180
	v_mul_f32_e32 v181, v57, v181
	v_mul_f32_e32 v182, v58, v182
	v_mul_f32_e32 v183, v59, v183
	v_cvt_pk_bf16_f32 v192, v176, v177
	v_cvt_pk_bf16_f32 v193, v178, v179
	v_cvt_pk_bf16_f32 v194, v180, v181
	v_cvt_pk_bf16_f32 v195, v182, v183
	v_add_u32_e32 v200, 0xb0000, v248
	global_store_dwordx4 v200, v[192:195], s[48:49]
	v_pk_mul_f32 v[36:37], v[36:37], v[158:159] op_sel_hi:[1,0]
	v_pk_mul_f32 v[38:39], v[38:39], v[158:159] op_sel_hi:[1,0]
	v_pk_mul_f32 v[32:33], v[32:33], v[158:159] op_sel_hi:[1,0]
	v_pk_mul_f32 v[34:35], v[34:35], v[158:159] op_sel_hi:[1,0]
	v_pk_mul_f32 v[44:45], v[44:45], v[158:159] op_sel_hi:[1,0]
	v_pk_mul_f32 v[46:47], v[46:47], v[158:159] op_sel_hi:[1,0]
	v_pk_mul_f32 v[40:41], v[40:41], v[158:159] op_sel_hi:[1,0]
	v_pk_mul_f32 v[42:43], v[42:43], v[158:159] op_sel_hi:[1,0]
	v_mul_f32_e32 v184, 0xbfb8aa3b, v36
	v_mul_f32_e32 v185, 0xbfb8aa3b, v37
	v_mul_f32_e32 v186, 0xbfb8aa3b, v38
	v_mul_f32_e32 v187, 0xbfb8aa3b, v39
	v_mul_f32_e32 v188, 0xbfb8aa3b, v32
	v_mul_f32_e32 v189, 0xbfb8aa3b, v33
	v_mul_f32_e32 v190, 0xbfb8aa3b, v34
	v_mul_f32_e32 v191, 0xbfb8aa3b, v35
	v_exp_f32_e32 v184, v184
	v_exp_f32_e32 v185, v185
	v_exp_f32_e32 v186, v186
	v_exp_f32_e32 v187, v187
	v_exp_f32_e32 v188, v188
	v_exp_f32_e32 v189, v189
	v_exp_f32_e32 v190, v190
	v_exp_f32_e32 v191, v191
	v_add_f32_e32 v184, 1.0, v184
	v_add_f32_e32 v185, 1.0, v185
	v_add_f32_e32 v186, 1.0, v186
	v_add_f32_e32 v187, 1.0, v187
	v_add_f32_e32 v188, 1.0, v188
	v_add_f32_e32 v189, 1.0, v189
	v_add_f32_e32 v190, 1.0, v190
	v_add_f32_e32 v191, 1.0, v191
	v_rcp_f32_e32 v184, v184
	v_rcp_f32_e32 v185, v185
	v_rcp_f32_e32 v186, v186
	v_rcp_f32_e32 v187, v187
	v_rcp_f32_e32 v188, v188
	v_rcp_f32_e32 v189, v189
	v_rcp_f32_e32 v190, v190
	v_rcp_f32_e32 v191, v191
	v_mul_f32_e32 v184, v36, v184
	v_mul_f32_e32 v185, v37, v185
	v_mul_f32_e32 v186, v38, v186
	v_mul_f32_e32 v187, v39, v187
	v_mul_f32_e32 v188, v32, v188
	v_mul_f32_e32 v189, v33, v189
	v_mul_f32_e32 v190, v34, v190
	v_mul_f32_e32 v191, v35, v191
	v_mul_f32_e32 v184, v44, v184
	v_mul_f32_e32 v185, v45, v185
	v_mul_f32_e32 v186, v46, v186
	v_mul_f32_e32 v187, v47, v187
	v_mul_f32_e32 v188, v40, v188
	v_mul_f32_e32 v189, v41, v189
; #define PG8_WAIT_V(n) asm volatile("s_waitcnt vmcnt(" #n ")" ::: "memory")
; template <class Epi, class Sched, bool ALIGN_EPI = false, bool SP2 = false>
; __device__ __forceinline__ void gemm_phase(PG8_LAS unsigned char* lds, const Gemm g, const Sched& S, const Epi& E) {
;     ...
;         for (int t = 0; t < nt; t += 2) {
;             const bool last = (t == nt - 2);
;             const char* a1 = cA + (size_t)(t + 1) * kstep;
;             const char* a2 = last ? nA : cA + (size_t)(t + 2) * kstep; const char* b2 = last ? nB : cB + (size_t)(t + 2) * kstep;
;             const char* a3 = a2 + kstep; const char* b3 = b2 + kstep;
;             if (last && has_next) S.a_ready(nxt);
;             if constexpr (SP2) {
;             PG8_LDB(B0, 0, 0); PG8_LDB(B1, 0, 1); PG8_SCHED; PG8_LDA(At, 0, 0); PG8_STAGE(PG8_SA(1, 1), a1 + hstep, voffA);
;             PG8_WAIT_V(8); PG8_WAIT_L(0); PG8_BAR; PG8_MMA(0, 0, At, B0); PG8_MMA(0, 1, At, B1); PG8_BAR; PG8_SCHED;
;             PG8_LDA(At, 0, 1); PG8_STAGE(PG8_SB(0, 0), b2, voffB); PG8_STAGE(PG8_SB(0, 1), b2 + hstep, voffB); PG8_STAGE(PG8_SA(0, 0), a2, voffA);
;             PG8_WAIT_V(8); PG8_WAIT_L(0); PG8_BAR; PG8_MMA(1, 0, At, B0); PG8_MMA(1, 1, At, B1); PG8_BAR; PG8_SCHED;
;             PG8_LDB(B0, 1, 0); PG8_LDB(B1, 1, 1); PG8_SCHED; PG8_LDA(At, 1, 0); PG8_STAGE(PG8_SA(0, 1), a2 + hstep, voffA);
;             PG8_WAIT_V(8); PG8_WAIT_L(0); PG8_BAR; PG8_MMA(0, 0, At, B0); PG8_MMA(0, 1, At, B1); PG8_BAR; PG8_SCHED;
;             PG8_LDA(At, 1, 1); PG8_STAGE(PG8_SB(1, 0), b3, voffB); PG8_STAGE(PG8_SB(1, 1), b3 + hstep, voffB); PG8_STAGE(PG8_SA(1, 0), a3, voffA);
;     __device__ __forceinline__ void operator()(AccRef acc, const pg8::Unit& u, int wr, int wc, int fr, int fq) const {
;     ...
;             for (int m = 0; m < 4; ++m) {
;                 const int row = row0 + ai * 128 + m * 16;
;                 const float rs = rs_from(ssp + (size_t)row * 16, 4, 1.0f / 1024.0f);
;                 f32x4 o[2];
; #pragma unroll
;                 for (int n = 0; n < 2; ++n)
; #pragma unroll
;                     for (int j = 0; j < 4; ++j) {
;                         const float g = acc[ai][0][m][n][j] * rs, up = acc[ai][1][m][n][j] * rs;
;                         o[n][j] = g * __builtin_amdgcn_rcpf(1.0f + __expf(-g)) * up;
;                     }
;                 *(u32x4*)(act + (size_t)row * FF + col0) = pack8(o[0], o[1]);
	v_mul_f32_e32 v190, v42, v190
	v_mul_f32_e32 v191, v43, v191
	v_cvt_pk_bf16_f32 v196, v184, v185
	v_cvt_pk_bf16_f32 v197, v186, v187
	v_cvt_pk_bf16_f32 v198, v188, v189
	v_cvt_pk_bf16_f32 v199, v190, v191
	v_add_u32_e32 v201, 0xc6000, v248
	global_store_dwordx4 v201, v[196:199], s[48:49]
	v_pk_mul_f32 v[20:21], v[20:21], v[162:163] op_sel_hi:[1,0]
	v_pk_mul_f32 v[22:23], v[22:23], v[162:163] op_sel_hi:[1,0]
	v_pk_mul_f32 v[16:17], v[16:17], v[162:163] op_sel_hi:[1,0]
	v_pk_mul_f32 v[18:19], v[18:19], v[162:163] op_sel_hi:[1,0]
	v_pk_mul_f32 v[28:29], v[28:29], v[162:163] op_sel_hi:[1,0]
	v_pk_mul_f32 v[30:31], v[30:31], v[162:163] op_sel_hi:[1,0]
	v_pk_mul_f32 v[24:25], v[24:25], v[162:163] op_sel_hi:[1,0]
	v_pk_mul_f32 v[26:27], v[26:27], v[162:163] op_sel_hi:[1,0]
	v_mul_f32_e32 v176, 0xbfb8aa3b, v20
	v_mul_f32_e32 v177, 0xbfb8aa3b, v21
	v_mul_f32_e32 v178, 0xbfb8aa3b, v22
	v_mul_f32_e32 v179, 0xbfb8aa3b, v23
	v_mul_f32_e32 v180, 0xbfb8aa3b, v16
	v_mul_f32_e32 v181, 0xbfb8aa3b, v17
	v_mul_f32_e32 v182, 0xbfb8aa3b, v18
	v_mul_f32_e32 v183, 0xbfb8aa3b, v19
	v_exp_f32_e32 v176, v176
	v_exp_f32_e32 v177, v177
	v_exp_f32_e32 v178, v178
	v_exp_f32_e32 v179, v179
	v_exp_f32_e32 v180, v180
	v_exp_f32_e32 v181, v181
	v_exp_f32_e32 v182, v182
	v_exp_f32_e32 v183, v183
	v_add_f32_e32 v176, 1.0, v176
	v_add_f32_e32 v177, 1.0, v177
	v_add_f32_e32 v178, 1.0, v178
	v_add_f32_e32 v179, 1.0, v179
	v_add_f32_e32 v180, 1.0, v180
	v_add_f32_e32 v181, 1.0, v181
	v_add_f32_e32 v182, 1.0, v182
	v_add_f32_e32 v183, 1.0, v183
	v_rcp_f32_e32 v176, v176
	v_rcp_f32_e32 v177, v177
	v_rcp_f32_e32 v178, v178
	v_rcp_f32_e32 v179, v179
	v_rcp_f32_e32 v180, v180
	v_rcp_f32_e32 v181, v181
	v_rcp_f32_e32 v182, v182
	v_rcp_f32_e32 v183, v183
	v_mul_f32_e32 v176, v20, v176
	v_mul_f32_e32 v177, v21, v177
	v_mul_f32_e32 v178, v22, v178
	v_mul_f32_e32 v179, v23, v179
	v_mul_f32_e32 v180, v16, v180
	v_mul_f32_e32 v181, v17, v181
	v_mul_f32_e32 v182, v18, v182
	v_mul_f32_e32 v183, v19, v183
	v_mul_f32_e32 v176, v28, v176
	v_mul_f32_e32 v177, v29, v177
	v_mul_f32_e32 v178, v30, v178
	v_mul_f32_e32 v179, v31, v179
	v_mul_f32_e32 v180, v24, v180
	v_mul_f32_e32 v181, v25, v181
	v_mul_f32_e32 v182, v26, v182
	v_mul_f32_e32 v183, v27, v183
	v_cvt_pk_bf16_f32 v192, v176, v177
	v_cvt_pk_bf16_f32 v193, v178, v179
	v_cvt_pk_bf16_f32 v194, v180, v181
	v_cvt_pk_bf16_f32 v195, v182, v183
	v_add_u32_e32 v200, 0xdc000, v248
	global_store_dwordx4 v200, v[192:195], s[48:49]
	v_pk_mul_f32 v[4:5], v[4:5], v[166:167] op_sel_hi:[1,0]
	v_pk_mul_f32 v[6:7], v[6:7], v[166:167] op_sel_hi:[1,0]
	v_pk_mul_f32 v[0:1], v[0:1], v[166:167] op_sel_hi:[1,0]
	v_pk_mul_f32 v[2:3], v[2:3], v[166:167] op_sel_hi:[1,0]
	v_pk_mul_f32 v[12:13], v[12:13], v[166:167] op_sel_hi:[1,0]
	v_pk_mul_f32 v[14:15], v[14:15], v[166:167] op_sel_hi:[1,0]
	v_pk_mul_f32 v[8:9], v[8:9], v[166:167] op_sel_hi:[1,0]
	v_pk_mul_f32 v[10:11], v[10:11], v[166:167] op_sel_hi:[1,0]
	v_mul_f32_e32 v184, 0xbfb8aa3b, v4
	v_mul_f32_e32 v185, 0xbfb8aa3b, v5
	v_mul_f32_e32 v186, 0xbfb8aa3b, v6
	v_mul_f32_e32 v187, 0xbfb8aa3b, v7
	v_mul_f32_e32 v188, 0xbfb8aa3b, v0
	v_mul_f32_e32 v189, 0xbfb8aa3b, v1
	v_mul_f32_e32 v190, 0xbfb8aa3b, v2
	v_mul_f32_e32 v191, 0xbfb8aa3b, v3
	v_exp_f32_e32 v184, v184
	v_exp_f32_e32 v185, v185
	v_exp_f32_e32 v186, v186
	v_exp_f32_e32 v187, v187
	v_exp_f32_e32 v188, v188
	v_exp_f32_e32 v189, v189
	v_exp_f32_e32 v190, v190
	v_exp_f32_e32 v191, v191
	v_add_f32_e32 v184, 1.0, v184
	v_add_f32_e32 v185, 1.0, v185
	v_add_f32_e32 v186, 1.0, v186
	v_add_f32_e32 v187, 1.0, v187
	v_add_f32_e32 v188, 1.0, v188
	v_add_f32_e32 v189, 1.0, v189
	v_add_f32_e32 v190, 1.0, v190
	v_add_f32_e32 v191, 1.0, v191
	v_rcp_f32_e32 v184, v184
	v_rcp_f32_e32 v185, v185
	v_rcp_f32_e32 v186, v186
	v_rcp_f32_e32 v187, v187
	v_rcp_f32_e32 v188, v188
	v_rcp_f32_e32 v189, v189
	v_rcp_f32_e32 v190, v190
	v_rcp_f32_e32 v191, v191
	v_mul_f32_e32 v184, v4, v184
	v_mul_f32_e32 v185, v5, v185
	v_mul_f32_e32 v186, v6, v186
	v_mul_f32_e32 v187, v7, v187
	v_mul_f32_e32 v188, v0, v188
	v_mul_f32_e32 v189, v1, v189
	v_mul_f32_e32 v190, v2, v190
	v_mul_f32_e32 v191, v3, v191
	v_mul_f32_e32 v184, v12, v184
	v_mul_f32_e32 v185, v13, v185
	v_mul_f32_e32 v186, v14, v186
	v_mul_f32_e32 v187, v15, v187
	v_mul_f32_e32 v188, v8, v188
	v_mul_f32_e32 v189, v9, v189
	v_mul_f32_e32 v190, v10, v190
	v_mul_f32_e32 v191, v11, v191
	v_cvt_pk_bf16_f32 v196, v184, v185
	v_cvt_pk_bf16_f32 v197, v186, v187
	v_cvt_pk_bf16_f32 v198, v188, v189
	v_cvt_pk_bf16_f32 v199, v190, v191
	v_add_u32_e32 v201, 0xf2000, v248
	global_store_dwordx4 v201, v[196:199], s[48:49]
	s_and_b64 vcc, exec, s[2:3]
	s_mov_b64 s[2:3], -1
	s_cbranch_vccnz .LBB0_1308
	s_andn2_b64 vcc, exec, s[12:13]
	s_cbranch_vccnz .LBB0_1307
	s_barrier
	s_branch .LBB0_1307

;     __host__ __device__ bool next(int i, Unit& u) const {
;         const long L = (long)i * G + c; if (L >= nwg) return false;
;         int wgid = (int)L; { const int q = nwg / NXCD, r = nwg % NXCD, xcd = wgid % NXCD, off = wgid / NXCD; wgid = (xcd < r ? xcd * (q + 1) : r * (q + 1) + (xcd - r) * q) + off; }
;         const int nig = WGM * nN, gid = wgid / nig, fm = gid * WGM, gsz = (nM - fm) < WGM ? (nM - fm) : WGM;
;         u.pm = fm + ((wgid % nig) % gsz); u.pn = (wgid % nig) / gsz; return true;
;     }
;     __device__ __forceinline__ void operator()(AccRef acc, const pg8::Unit& u, int wr, int wc, int fr, int fq) const {
;     ...
;                 const int row = row0 + ai * 128 + m * 16;
;                 const float rs = rs_from(ssp + (size_t)row * 16, 4, 1.0f / 1024.0f);
.LBB0_2473:
	v_lshl_add_u32 v246, s58, 8, v146
	v_and_b32_e32 v247, 24, v148
	v_lshlrev_b32_e32 v247, 1, v247
	v_lshl_add_u32 v247, v246, 6, v247
	global_load_dwordx4 v[230:233], v247, s[46:47]
	global_load_dwordx4 v[234:237], v247, s[46:47] offset:1024
	global_load_dwordx4 v[238:241], v247, s[46:47] offset:2048
	global_load_dwordx4 v[242:245], v247, s[46:47] offset:3072
	s_add_i32 s35, s35, 1
	s_mul_i32 s0, s35, s40
	s_mul_hi_u32 s1, s35, s41
	s_add_i32 s1, s1, s0
	s_mul_i32 s0, s35, s41
	s_add_u32 s2, s0, s18
	s_addc_u32 s3, s1, s17
	v_cmp_gt_i64_e32 vcc, s[2:3], v[142:143]
	v_cmp_lt_i64_e64 s[0:1], s[2:3], v[140:141]
	s_cbranch_vccnz .LBB0_2475
	s_ashr_i32 s3, s2, 31
	s_lshr_b32 s3, s3, 29
	s_add_i32 s3, s2, s3
	s_ashr_i32 s24, s3, 3
	s_and_b32 s3, s3, -8
	s_sub_i32 s2, s2, s3
	s_cmp_lt_i32 s2, 0
	s_cselect_b32 s3, s19, 0x160
	s_mul_i32 s2, s3, s2
	s_add_i32 s2, s2, s24
	s_mul_hi_i32 s3, s2, 0x2e8ba2e9
	s_lshr_b32 s24, s3, 31
	s_ashr_i32 s3, s3, 5
	s_add_i32 s3, s3, s24
	s_lshl_b32 s24, s3, 3
	s_sub_i32 s25, 0x80, s24
	s_min_i32 s25, s25, 8
	s_abs_i32 s56, s25
	v_cvt_f32_u32_e32 v0, s56
	s_sub_i32 s60, 0, s56
	s_mulk_i32 s3, 0xb0
	s_sub_i32 s2, s2, s3
	v_rcp_iflag_f32_e32 v0, v0
	s_abs_i32 s3, s2
	s_xor_b32 s57, s2, s25
	s_ashr_i32 s57, s57, 31
	v_mul_f32_e32 v0, 0x4f7ffffe, v0
	v_cvt_u32_f32_e32 v0, v0
	s_nop 0
	v_readfirstlane_b32 s61, v0
	s_mul_i32 s60, s60, s61
	s_mul_hi_u32 s60, s61, s60
	s_add_i32 s61, s61, s60
	s_mul_hi_u32 s60, s3, s61
	s_mul_i32 s61, s60, s56
	s_sub_i32 s3, s3, s61
	s_add_i32 s62, s60, 1
	s_sub_i32 s61, s3, s56
	s_cmp_ge_u32 s3, s56
	s_cselect_b32 s60, s62, s60
	s_cselect_b32 s3, s61, s3
	s_add_i32 s61, s60, 1
	s_cmp_ge_u32 s3, s56
	s_cselect_b32 s3, s61, s60
	s_xor_b32 s3, s3, s57
	s_sub_i32 s56, s3, s57
	s_mul_i32 s3, s56, s25
	s_sub_i32 s2, s2, s3
	s_add_i32 s57, s2, s24

;     __device__ __forceinline__ void operator()(const f32x4 (&acc)[2], int srow, int cgp, int kq) const { one(acc[0], srow, 2 * cgp, kq); one(acc[1], srow, 2 * cgp + 1, kq); }
; __device__ __forceinline__ float rs_from(const float* p, int n4, float inv_n) {
;     float s = 0.f;
;     for (int i = 0; i < n4; ++i) { const f32x4 v = *(const f32x4*)(p + 4 * i); s += (v[0] + v[1]) + (v[2] + v[3]); }
;     return rsqrtf(s * inv_n + EPS);
;     __device__ __forceinline__ void operator()(AccRef acc, const pg8::Unit& u, int wr, int wc, int fr, int fq) const {
;         const int row0 = u.pm * 256 + wr * 64 + fr, col0 = u.pn * 128 + wc * 32 + 8 * fq;
; #pragma unroll
;         for (int ai = 0; ai < 2; ++ai)
; #pragma unroll
;             for (int m = 0; m < 4; ++m) {
;                 const int row = row0 + ai * 128 + m * 16;
;                 const float rs = rs_from(ssp + (size_t)row * 16, 4, 1.0f / 1024.0f);
;                 f32x4 o[2];
; #pragma unroll
;                 for (int n = 0; n < 2; ++n)
; #pragma unroll
;                     for (int j = 0; j < 4; ++j) {
;                         const float g = acc[ai][0][m][n][j] * rs, up = acc[ai][1][m][n][j] * rs;
;                         o[n][j] = g * __builtin_amdgcn_rcpf(1.0f + __expf(-g)) * up;
;                     }
;                 *(u32x4*)(act + (size_t)row * FF + col0) = pack8(o[0], o[1]);
.LBB0_2484:
	v_add_u32_e32 v249, 0x2000, v247
	global_load_dwordx4 v[154:157], v249, s[46:47]
	global_load_dwordx4 v[158:161], v249, s[46:47] offset:1024
	global_load_dwordx4 v[162:165], v249, s[46:47] offset:2048
	global_load_dwordx4 v[166:169], v249, s[46:47] offset:3072
	v_mbcnt_lo_u32_b32 v170, -1, 0
	v_mbcnt_hi_u32_b32 v170, -1, v170
	v_xor_b32_e32 v171, 16, v170
	v_xor_b32_e32 v172, 32, v170
	v_lshlrev_b32_e32 v171, 2, v171
	v_lshlrev_b32_e32 v172, 2, v172
	v_lshl_or_b32 v173, s59, 7, v148
	v_lshlrev_b32_e32 v173, 1, v173
	v_mad_u32_u24 v248, v246, s51, v173
	s_waitcnt vmcnt(12)
	v_add_f32_e32 v230, v230, v231
	v_add_f32_e32 v232, v232, v233
	v_add_f32_e32 v234, v234, v235
	v_add_f32_e32 v236, v236, v237
	v_add_f32_e32 v238, v238, v239
	v_add_f32_e32 v240, v240, v241
	v_add_f32_e32 v242, v242, v243
	v_add_f32_e32 v244, v244, v245
	v_add_f32_e32 v230, v230, v232
	v_add_f32_e32 v234, v234, v236
	v_add_f32_e32 v238, v238, v240
	v_add_f32_e32 v242, v242, v244
	ds_bpermute_b32 v231, v171, v230
	ds_bpermute_b32 v235, v171, v234
	ds_bpermute_b32 v239, v171, v238
	ds_bpermute_b32 v243, v171, v242
	s_waitcnt lgkmcnt(0)
	v_add_f32_e32 v230, v230, v231
	v_add_f32_e32 v234, v234, v235
	v_add_f32_e32 v238, v238, v239
	v_add_f32_e32 v242, v242, v243
	ds_bpermute_b32 v231, v172, v230
	ds_bpermute_b32 v235, v172, v234
	ds_bpermute_b32 v239, v172, v238
	ds_bpermute_b32 v243, v172, v242
	s_waitcnt lgkmcnt(0)
	v_add_f32_e32 v230, v230, v231
	v_add_f32_e32 v234, v234, v235
	v_add_f32_e32 v238, v238, v239
	v_add_f32_e32 v242, v242, v243
	v_fmamk_f32 v230, v230, 0x3a800000, v152
	v_fmamk_f32 v234, v234, 0x3a800000, v152
	v_fmamk_f32 v238, v238, 0x3a800000, v152
	v_fmamk_f32 v242, v242, 0x3a800000, v152
	v_rsq_f32_e32 v230, v230
	v_rsq_f32_e32 v234, v234
	v_rsq_f32_e32 v238, v238
	v_rsq_f32_e32 v242, v242
	s_nop 0
	v_pk_mul_f32 v[116:117], v[116:117], v[230:231] op_sel_hi:[1,0]
	v_pk_mul_f32 v[118:119], v[118:119], v[230:231] op_sel_hi:[1,0]
	v_pk_mul_f32 v[112:113], v[112:113], v[230:231] op_sel_hi:[1,0]
	v_pk_mul_f32 v[114:115], v[114:115], v[230:231] op_sel_hi:[1,0]
	v_pk_mul_f32 v[124:125], v[124:125], v[230:231] op_sel_hi:[1,0]
	v_pk_mul_f32 v[126:127], v[126:127], v[230:231] op_sel_hi:[1,0]
	v_pk_mul_f32 v[120:121], v[120:121], v[230:231] op_sel_hi:[1,0]
	v_pk_mul_f32 v[122:123], v[122:123], v[230:231] op_sel_hi:[1,0]
	v_mul_f32_e32 v176, 0xbfb8aa3b, v116
	v_mul_f32_e32 v177, 0xbfb8aa3b, v117
	v_mul_f32_e32 v178, 0xbfb8aa3b, v118
	v_mul_f32_e32 v179, 0xbfb8aa3b, v119
	v_mul_f32_e32 v180, 0xbfb8aa3b, v112
	v_mul_f32_e32 v181, 0xbfb8aa3b, v113
	v_mul_f32_e32 v182, 0xbfb8aa3b, v114
	v_mul_f32_e32 v183, 0xbfb8aa3b, v115
	v_exp_f32_e32 v176, v176
	v_exp_f32_e32 v177, v177
	v_exp_f32_e32 v178, v178
	v_exp_f32_e32 v179, v179
	v_exp_f32_e32 v180, v180
	v_exp_f32_e32 v181, v181
	v_exp_f32_e32 v182, v182
	v_exp_f32_e32 v183, v183
	v_add_f32_e32 v176, 1.0, v176
	v_add_f32_e32 v177, 1.0, v177
	v_add_f32_e32 v178, 1.0, v178
	v_add_f32_e32 v179, 1.0, v179
	v_add_f32_e32 v180, 1.0, v180
	v_add_f32_e32 v181, 1.0, v181
	v_add_f32_e32 v182, 1.0, v182
	v_add_f32_e32 v183, 1.0, v183
	v_rcp_f32_e32 v176, v176
	v_rcp_f32_e32 v177, v177
	v_rcp_f32_e32 v178, v178
	v_rcp_f32_e32 v179, v179
	v_rcp_f32_e32 v180, v180
	v_rcp_f32_e32 v181, v181
	v_rcp_f32_e32 v182, v182
	v_rcp_f32_e32 v183, v183
	v_mul_f32_e32 v176, v116, v176
	v_mul_f32_e32 v177, v117, v177
	v_mul_f32_e32 v178, v118, v178
	v_mul_f32_e32 v179, v119, v179
	v_mul_f32_e32 v180, v112, v180
	v_mul_f32_e32 v181, v113, v181
	v_mul_f32_e32 v182, v114, v182
	v_mul_f32_e32 v183, v115, v183
	v_mul_f32_e32 v176, v124, v176
	v_mul_f32_e32 v177, v125, v177
	v_mul_f32_e32 v178, v126, v178
	v_mul_f32_e32 v179, v127, v179
	v_mul_f32_e32 v180, v120, v180
	v_mul_f32_e32 v181, v121, v181
	v_mul_f32_e32 v182, v122, v182
	v_mul_f32_e32 v183, v123, v183
	v_cvt_pk_bf16_f32 v192, v176, v177
	v_cvt_pk_bf16_f32 v193, v178, v179
	v_cvt_pk_bf16_f32 v194, v180, v181
	v_cvt_pk_bf16_f32 v195, v182, v183
	v_mov_b32_e32 v200, v248
	global_store_dwordx4 v200, v[192:195], s[48:49]
	v_pk_mul_f32 v[100:101], v[100:101], v[234:235] op_sel_hi:[1,0]
	v_pk_mul_f32 v[102:103], v[102:103], v[234:235] op_sel_hi:[1,0]
	v_pk_mul_f32 v[96:97], v[96:97], v[234:235] op_sel_hi:[1,0]
	v_pk_mul_f32 v[98:99], v[98:99], v[234:235] op_sel_hi:[1,0]
	v_pk_mul_f32 v[108:109], v[108:109], v[234:235] op_sel_hi:[1,0]
	v_pk_mul_f32 v[110:111], v[110:111], v[234:235] op_sel_hi:[1,0]
	v_pk_mul_f32 v[104:105], v[104:105], v[234:235] op_sel_hi:[1,0]
	v_pk_mul_f32 v[106:107], v[106:107], v[234:235] op_sel_hi:[1,0]
	v_mul_f32_e32 v184, 0xbfb8aa3b, v100
	v_mul_f32_e32 v185, 0xbfb8aa3b, v101
	v_mul_f32_e32 v186, 0xbfb8aa3b, v102
	v_mul_f32_e32 v187, 0xbfb8aa3b, v103
	v_mul_f32_e32 v188, 0xbfb8aa3b, v96
	v_mul_f32_e32 v189, 0xbfb8aa3b, v97
	v_mul_f32_e32 v190, 0xbfb8aa3b, v98
	v_mul_f32_e32 v191, 0xbfb8aa3b, v99
	v_exp_f32_e32 v184, v184
	v_exp_f32_e32 v185, v185
	v_exp_f32_e32 v186, v186
	v_exp_f32_e32 v187, v187
	v_exp_f32_e32 v188, v188
	v_exp_f32_e32 v189, v189
	v_exp_f32_e32 v190, v190
	v_exp_f32_e32 v191, v191
	v_add_f32_e32 v184, 1.0, v184
	v_add_f32_e32 v185, 1.0, v185
	v_add_f32_e32 v186, 1.0, v186
	v_add_f32_e32 v187, 1.0, v187
	v_add_f32_e32 v188, 1.0, v188
	v_add_f32_e32 v189, 1.0, v189
	v_add_f32_e32 v190, 1.0, v190
	v_add_f32_e32 v191, 1.0, v191
	v_rcp_f32_e32 v184, v184
	v_rcp_f32_e32 v185, v185
	v_rcp_f32_e32 v186, v186
	v_rcp_f32_e32 v187, v187
	v_rcp_f32_e32 v188, v188
	v_rcp_f32_e32 v189, v189
	v_rcp_f32_e32 v190, v190
	v_rcp_f32_e32 v191, v191
	v_mul_f32_e32 v184, v100, v184
	v_mul_f32_e32 v185, v101, v185
	v_mul_f32_e32 v186, v102, v186
	v_mul_f32_e32 v187, v103, v187
;     __device__ __forceinline__ void operator()(AccRef acc, const pg8::Unit& u, int wr, int wc, int fr, int fq) const {
;     ...
;         for (int ai = 0; ai < 2; ++ai)
; #pragma unroll
;             for (int m = 0; m < 4; ++m) {
;                 const int row = row0 + ai * 128 + m * 16;
;                 const float rs = rs_from(ssp + (size_t)row * 16, 4, 1.0f / 1024.0f);
;                 f32x4 o[2];
; #pragma unroll
;                 for (int n = 0; n < 2; ++n)
; #pragma unroll
;                     for (int j = 0; j < 4; ++j) {
;                         const float g = acc[ai][0][m][n][j] * rs, up = acc[ai][1][m][n][j] * rs;
;                         o[n][j] = g * __builtin_amdgcn_rcpf(1.0f + __expf(-g)) * up;
;                     }
;                 *(u32x4*)(act + (size_t)row * FF + col0) = pack8(o[0], o[1]);
	v_mul_f32_e32 v188, v96, v188
	v_mul_f32_e32 v189, v97, v189
	v_mul_f32_e32 v190, v98, v190
	v_mul_f32_e32 v191, v99, v191
	v_mul_f32_e32 v184, v108, v184
	v_mul_f32_e32 v185, v109, v185
	v_mul_f32_e32 v186, v110, v186
	v_mul_f32_e32 v187, v111, v187
	v_mul_f32_e32 v188, v104, v188
	v_mul_f32_e32 v189, v105, v189
	v_mul_f32_e32 v190, v106, v190
	v_mul_f32_e32 v191, v107, v191
	v_cvt_pk_bf16_f32 v196, v184, v185
	v_cvt_pk_bf16_f32 v197, v186, v187
	v_cvt_pk_bf16_f32 v198, v188, v189
	v_cvt_pk_bf16_f32 v199, v190, v191
	v_add_u32_e32 v201, 0x16000, v248
	global_store_dwordx4 v201, v[196:199], s[48:49]
	v_pk_mul_f32 v[84:85], v[84:85], v[238:239] op_sel_hi:[1,0]
	v_pk_mul_f32 v[86:87], v[86:87], v[238:239] op_sel_hi:[1,0]
	v_pk_mul_f32 v[80:81], v[80:81], v[238:239] op_sel_hi:[1,0]
	v_pk_mul_f32 v[82:83], v[82:83], v[238:239] op_sel_hi:[1,0]
	v_pk_mul_f32 v[92:93], v[92:93], v[238:239] op_sel_hi:[1,0]
	v_pk_mul_f32 v[94:95], v[94:95], v[238:239] op_sel_hi:[1,0]
	v_pk_mul_f32 v[88:89], v[88:89], v[238:239] op_sel_hi:[1,0]
	v_pk_mul_f32 v[90:91], v[90:91], v[238:239] op_sel_hi:[1,0]
	v_mul_f32_e32 v176, 0xbfb8aa3b, v84
	v_mul_f32_e32 v177, 0xbfb8aa3b, v85
	v_mul_f32_e32 v178, 0xbfb8aa3b, v86
	v_mul_f32_e32 v179, 0xbfb8aa3b, v87
	v_mul_f32_e32 v180, 0xbfb8aa3b, v80
	v_mul_f32_e32 v181, 0xbfb8aa3b, v81
	v_mul_f32_e32 v182, 0xbfb8aa3b, v82
	v_mul_f32_e32 v183, 0xbfb8aa3b, v83
	v_exp_f32_e32 v176, v176
	v_exp_f32_e32 v177, v177
	v_exp_f32_e32 v178, v178
	v_exp_f32_e32 v179, v179
	v_exp_f32_e32 v180, v180
	v_exp_f32_e32 v181, v181
	v_exp_f32_e32 v182, v182
	v_exp_f32_e32 v183, v183
	v_add_f32_e32 v176, 1.0, v176
	v_add_f32_e32 v177, 1.0, v177
	v_add_f32_e32 v178, 1.0, v178
	v_add_f32_e32 v179, 1.0, v179
	v_add_f32_e32 v180, 1.0, v180
	v_add_f32_e32 v181, 1.0, v181
	v_add_f32_e32 v182, 1.0, v182
	v_add_f32_e32 v183, 1.0, v183
	v_rcp_f32_e32 v176, v176
	v_rcp_f32_e32 v177, v177
	v_rcp_f32_e32 v178, v178
	v_rcp_f32_e32 v179, v179
	v_rcp_f32_e32 v180, v180
	v_rcp_f32_e32 v181, v181
	v_rcp_f32_e32 v182, v182
	v_rcp_f32_e32 v183, v183
	v_mul_f32_e32 v176, v84, v176
	v_mul_f32_e32 v177, v85, v177
	v_mul_f32_e32 v178, v86, v178
	v_mul_f32_e32 v179, v87, v179
	v_mul_f32_e32 v180, v80, v180
	v_mul_f32_e32 v181, v81, v181
	v_mul_f32_e32 v182, v82, v182
	v_mul_f32_e32 v183, v83, v183
	v_mul_f32_e32 v176, v92, v176
	v_mul_f32_e32 v177, v93, v177
	v_mul_f32_e32 v178, v94, v178
	v_mul_f32_e32 v179, v95, v179
	v_mul_f32_e32 v180, v88, v180
	v_mul_f32_e32 v181, v89, v181
	v_mul_f32_e32 v182, v90, v182
	v_mul_f32_e32 v183, v91, v183
	v_cvt_pk_bf16_f32 v192, v176, v177
	v_cvt_pk_bf16_f32 v193, v178, v179
	v_cvt_pk_bf16_f32 v194, v180, v181
	v_cvt_pk_bf16_f32 v195, v182, v183
	v_add_u32_e32 v200, 0x2c000, v248
	global_store_dwordx4 v200, v[192:195], s[48:49]
	v_pk_mul_f32 v[68:69], v[68:69], v[242:243] op_sel_hi:[1,0]
	v_pk_mul_f32 v[70:71], v[70:71], v[242:243] op_sel_hi:[1,0]
	v_pk_mul_f32 v[64:65], v[64:65], v[242:243] op_sel_hi:[1,0]
	v_pk_mul_f32 v[66:67], v[66:67], v[242:243] op_sel_hi:[1,0]
	v_pk_mul_f32 v[76:77], v[76:77], v[242:243] op_sel_hi:[1,0]
	v_pk_mul_f32 v[78:79], v[78:79], v[242:243] op_sel_hi:[1,0]
	v_pk_mul_f32 v[72:73], v[72:73], v[242:243] op_sel_hi:[1,0]
	v_pk_mul_f32 v[74:75], v[74:75], v[242:243] op_sel_hi:[1,0]
	v_mul_f32_e32 v184, 0xbfb8aa3b, v68
	v_mul_f32_e32 v185, 0xbfb8aa3b, v69
	v_mul_f32_e32 v186, 0xbfb8aa3b, v70
	v_mul_f32_e32 v187, 0xbfb8aa3b, v71
	v_mul_f32_e32 v188, 0xbfb8aa3b, v64
	v_mul_f32_e32 v189, 0xbfb8aa3b, v65
	v_mul_f32_e32 v190, 0xbfb8aa3b, v66
	v_mul_f32_e32 v191, 0xbfb8aa3b, v67
	v_exp_f32_e32 v184, v184
	v_exp_f32_e32 v185, v185
	v_exp_f32_e32 v186, v186
	v_exp_f32_e32 v187, v187
	v_exp_f32_e32 v188, v188
	v_exp_f32_e32 v189, v189
	v_exp_f32_e32 v190, v190
	v_exp_f32_e32 v191, v191
	v_add_f32_e32 v184, 1.0, v184
	v_add_f32_e32 v185, 1.0, v185
	v_add_f32_e32 v186, 1.0, v186
	v_add_f32_e32 v187, 1.0, v187
	v_add_f32_e32 v188, 1.0, v188
	v_add_f32_e32 v189, 1.0, v189
	v_add_f32_e32 v190, 1.0, v190
	v_add_f32_e32 v191, 1.0, v191
	v_rcp_f32_e32 v184, v184
	v_rcp_f32_e32 v185, v185
	v_rcp_f32_e32 v186, v186
	v_rcp_f32_e32 v187, v187
	v_rcp_f32_e32 v188, v188
	v_rcp_f32_e32 v189, v189
	v_rcp_f32_e32 v190, v190
	v_rcp_f32_e32 v191, v191
	v_mul_f32_e32 v184, v68, v184
	v_mul_f32_e32 v185, v69, v185
	v_mul_f32_e32 v186, v70, v186
	v_mul_f32_e32 v187, v71, v187
	v_mul_f32_e32 v188, v64, v188
	v_mul_f32_e32 v189, v65, v189
	v_mul_f32_e32 v190, v66, v190
	v_mul_f32_e32 v191, v67, v191
	v_mul_f32_e32 v184, v76, v184
	v_mul_f32_e32 v185, v77, v185
	v_mul_f32_e32 v186, v78, v186
	v_mul_f32_e32 v187, v79, v187
	v_mul_f32_e32 v188, v72, v188
	v_mul_f32_e32 v189, v73, v189
	v_mul_f32_e32 v190, v74, v190
	v_mul_f32_e32 v191, v75, v191
	v_cvt_pk_bf16_f32 v196, v184, v185
	v_cvt_pk_bf16_f32 v197, v186, v187
	v_cvt_pk_bf16_f32 v198, v188, v189
	v_cvt_pk_bf16_f32 v199, v190, v191
	v_add_u32_e32 v201, 0x42000, v248
	global_store_dwordx4 v201, v[196:199], s[48:49]
	s_waitcnt vmcnt(4)
	v_add_f32_e32 v154, v154, v155
	v_add_f32_e32 v156, v156, v157
	v_add_f32_e32 v158, v158, v159
	v_add_f32_e32 v160, v160, v161
	v_add_f32_e32 v162, v162, v163
	v_add_f32_e32 v164, v164, v165
	v_add_f32_e32 v166, v166, v167
	v_add_f32_e32 v168, v168, v169
	v_add_f32_e32 v154, v154, v156
	v_add_f32_e32 v158, v158, v160
	v_add_f32_e32 v162, v162, v164
	v_add_f32_e32 v166, v166, v168
	ds_bpermute_b32 v155, v171, v154
	ds_bpermute_b32 v159, v171, v158
	ds_bpermute_b32 v163, v171, v162
	ds_bpermute_b32 v167, v171, v166
	s_waitcnt lgkmcnt(0)
; __device__ __forceinline__ float rs_from(const float* p, int n4, float inv_n) {
;     float s = 0.f;
;     for (int i = 0; i < n4; ++i) { const f32x4 v = *(const f32x4*)(p + 4 * i); s += (v[0] + v[1]) + (v[2] + v[3]); }
;     return rsqrtf(s * inv_n + EPS);
;     __device__ __forceinline__ void operator()(AccRef acc, const pg8::Unit& u, int wr, int wc, int fr, int fq) const {
;     ...
;         for (int ai = 0; ai < 2; ++ai)
; #pragma unroll
;             for (int m = 0; m < 4; ++m) {
;                 const int row = row0 + ai * 128 + m * 16;
;                 const float rs = rs_from(ssp + (size_t)row * 16, 4, 1.0f / 1024.0f);
;                 f32x4 o[2];
; #pragma unroll
;                 for (int n = 0; n < 2; ++n)
; #pragma unroll
;                     for (int j = 0; j < 4; ++j) {
;                         const float g = acc[ai][0][m][n][j] * rs, up = acc[ai][1][m][n][j] * rs;
;                         o[n][j] = g * __builtin_amdgcn_rcpf(1.0f + __expf(-g)) * up;
;                     }
;                 *(u32x4*)(act + (size_t)row * FF + col0) = pack8(o[0], o[1]);
	v_add_f32_e32 v154, v154, v155
	v_add_f32_e32 v158, v158, v159
	v_add_f32_e32 v162, v162, v163
	v_add_f32_e32 v166, v166, v167
	ds_bpermute_b32 v155, v172, v154
	ds_bpermute_b32 v159, v172, v158
	ds_bpermute_b32 v163, v172, v162
	ds_bpermute_b32 v167, v172, v166
	s_waitcnt lgkmcnt(0)
	v_add_f32_e32 v154, v154, v155
	v_add_f32_e32 v158, v158, v159
	v_add_f32_e32 v162, v162, v163
	v_add_f32_e32 v166, v166, v167
	v_fmamk_f32 v154, v154, 0x3a800000, v152
	v_fmamk_f32 v158, v158, 0x3a800000, v152
	v_fmamk_f32 v162, v162, 0x3a800000, v152
	v_fmamk_f32 v166, v166, 0x3a800000, v152
	v_rsq_f32_e32 v154, v154
	v_rsq_f32_e32 v158, v158
	v_rsq_f32_e32 v162, v162
	v_rsq_f32_e32 v166, v166
	s_nop 0
	v_pk_mul_f32 v[52:53], v[52:53], v[154:155] op_sel_hi:[1,0]
	v_pk_mul_f32 v[54:55], v[54:55], v[154:155] op_sel_hi:[1,0]
	v_pk_mul_f32 v[48:49], v[48:49], v[154:155] op_sel_hi:[1,0]
	v_pk_mul_f32 v[50:51], v[50:51], v[154:155] op_sel_hi:[1,0]
	v_pk_mul_f32 v[60:61], v[60:61], v[154:155] op_sel_hi:[1,0]
	v_pk_mul_f32 v[62:63], v[62:63], v[154:155] op_sel_hi:[1,0]
	v_pk_mul_f32 v[56:57], v[56:57], v[154:155] op_sel_hi:[1,0]
	v_pk_mul_f32 v[58:59], v[58:59], v[154:155] op_sel_hi:[1,0]
	v_mul_f32_e32 v176, 0xbfb8aa3b, v52
	v_mul_f32_e32 v177, 0xbfb8aa3b, v53
	v_mul_f32_e32 v178, 0xbfb8aa3b, v54
	v_mul_f32_e32 v179, 0xbfb8aa3b, v55
	v_mul_f32_e32 v180, 0xbfb8aa3b, v48
	v_mul_f32_e32 v181, 0xbfb8aa3b, v49
	v_mul_f32_e32 v182, 0xbfb8aa3b, v50
	v_mul_f32_e32 v183, 0xbfb8aa3b, v51
	v_exp_f32_e32 v176, v176
	v_exp_f32_e32 v177, v177
	v_exp_f32_e32 v178, v178
	v_exp_f32_e32 v179, v179
	v_exp_f32_e32 v180, v180
	v_exp_f32_e32 v181, v181
	v_exp_f32_e32 v182, v182
	v_exp_f32_e32 v183, v183
	v_add_f32_e32 v176, 1.0, v176
	v_add_f32_e32 v177, 1.0, v177
	v_add_f32_e32 v178, 1.0, v178
	v_add_f32_e32 v179, 1.0, v179
	v_add_f32_e32 v180, 1.0, v180
	v_add_f32_e32 v181, 1.0, v181
	v_add_f32_e32 v182, 1.0, v182
	v_add_f32_e32 v183, 1.0, v183
	v_rcp_f32_e32 v176, v176
	v_rcp_f32_e32 v177, v177
	v_rcp_f32_e32 v178, v178
	v_rcp_f32_e32 v179, v179
	v_rcp_f32_e32 v180, v180
	v_rcp_f32_e32 v181, v181
	v_rcp_f32_e32 v182, v182
	v_rcp_f32_e32 v183, v183
	v_mul_f32_e32 v176, v52, v176
	v_mul_f32_e32 v177, v53, v177
	v_mul_f32_e32 v178, v54, v178
	v_mul_f32_e32 v179, v55, v179
	v_mul_f32_e32 v180, v48, v180
	v_mul_f32_e32 v181, v49, v181
	v_mul_f32_e32 v182, v50, v182
	v_mul_f32_e32 v183, v51, v183
	v_mul_f32_e32 v176, v60, v176
	v_mul_f32_e32 v177, v61, v177
	v_mul_f32_e32 v178, v62, v178
	v_mul_f32_e32 v179, v63, v179
	v_mul_f32_e32 v180, v56, v180
	v_mul_f32_e32 v181, v57, v181
	v_mul_f32_e32 v182, v58, v182
	v_mul_f32_e32 v183, v59, v183
	v_cvt_pk_bf16_f32 v192, v176, v177
	v_cvt_pk_bf16_f32 v193, v178, v179
	v_cvt_pk_bf16_f32 v194, v180, v181
	v_cvt_pk_bf16_f32 v195, v182, v183
	v_add_u32_e32 v200, 0xb0000, v248
	global_store_dwordx4 v200, v[192:195], s[48:49]
	v_pk_mul_f32 v[36:37], v[36:37], v[158:159] op_sel_hi:[1,0]
	v_pk_mul_f32 v[38:39], v[38:39], v[158:159] op_sel_hi:[1,0]
	v_pk_mul_f32 v[32:33], v[32:33], v[158:159] op_sel_hi:[1,0]
	v_pk_mul_f32 v[34:35], v[34:35], v[158:159] op_sel_hi:[1,0]
	v_pk_mul_f32 v[44:45], v[44:45], v[158:159] op_sel_hi:[1,0]
	v_pk_mul_f32 v[46:47], v[46:47], v[158:159] op_sel_hi:[1,0]
	v_pk_mul_f32 v[40:41], v[40:41], v[158:159] op_sel_hi:[1,0]
	v_pk_mul_f32 v[42:43], v[42:43], v[158:159] op_sel_hi:[1,0]
	v_mul_f32_e32 v184, 0xbfb8aa3b, v36
	v_mul_f32_e32 v185, 0xbfb8aa3b, v37
	v_mul_f32_e32 v186, 0xbfb8aa3b, v38
	v_mul_f32_e32 v187, 0xbfb8aa3b, v39
	v_mul_f32_e32 v188, 0xbfb8aa3b, v32
	v_mul_f32_e32 v189, 0xbfb8aa3b, v33
	v_mul_f32_e32 v190, 0xbfb8aa3b, v34
	v_mul_f32_e32 v191, 0xbfb8aa3b, v35
	v_exp_f32_e32 v184, v184
	v_exp_f32_e32 v185, v185
	v_exp_f32_e32 v186, v186
	v_exp_f32_e32 v187, v187
	v_exp_f32_e32 v188, v188
	v_exp_f32_e32 v189, v189
	v_exp_f32_e32 v190, v190
	v_exp_f32_e32 v191, v191
	v_add_f32_e32 v184, 1.0, v184
	v_add_f32_e32 v185, 1.0, v185
	v_add_f32_e32 v186, 1.0, v186
	v_add_f32_e32 v187, 1.0, v187
	v_add_f32_e32 v188, 1.0, v188
	v_add_f32_e32 v189, 1.0, v189
	v_add_f32_e32 v190, 1.0, v190
	v_add_f32_e32 v191, 1.0, v191
	v_rcp_f32_e32 v184, v184
	v_rcp_f32_e32 v185, v185
	v_rcp_f32_e32 v186, v186
	v_rcp_f32_e32 v187, v187
	v_rcp_f32_e32 v188, v188
	v_rcp_f32_e32 v189, v189
	v_rcp_f32_e32 v190, v190
	v_rcp_f32_e32 v191, v191
	v_mul_f32_e32 v184, v36, v184
	v_mul_f32_e32 v185, v37, v185
	v_mul_f32_e32 v186, v38, v186
	v_mul_f32_e32 v187, v39, v187
	v_mul_f32_e32 v188, v32, v188
	v_mul_f32_e32 v189, v33, v189
	v_mul_f32_e32 v190, v34, v190
	v_mul_f32_e32 v191, v35, v191
	v_mul_f32_e32 v184, v44, v184
	v_mul_f32_e32 v185, v45, v185
	v_mul_f32_e32 v186, v46, v186
	v_mul_f32_e32 v187, v47, v187
	v_mul_f32_e32 v188, v40, v188
	v_mul_f32_e32 v189, v41, v189
; #define PG8_WAIT_V(n) asm volatile("s_waitcnt vmcnt(" #n ")" ::: "memory")
; template <class Epi, class Sched, bool ALIGN_EPI = false, bool SP2 = false>
; __device__ __forceinline__ void gemm_phase(PG8_LAS unsigned char* lds, const Gemm g, const Sched& S, const Epi& E) {
;     ...
;         for (int t = 0; t < nt; t += 2) {
;             const bool last = (t == nt - 2);
;             const char* a1 = cA + (size_t)(t + 1) * kstep;
;             const char* a2 = last ? nA : cA + (size_t)(t + 2) * kstep; const char* b2 = last ? nB : cB + (size_t)(t + 2) * kstep;
;             const char* a3 = a2 + kstep; const char* b3 = b2 + kstep;
;             if (last && has_next) S.a_ready(nxt);
;             if constexpr (SP2) {
;             PG8_LDB(B0, 0, 0); PG8_LDB(B1, 0, 1); PG8_SCHED; PG8_LDA(At, 0, 0); PG8_STAGE(PG8_SA(1, 1), a1 + hstep, voffA);
;             PG8_WAIT_V(8); PG8_WAIT_L(0); PG8_BAR; PG8_MMA(0, 0, At, B0); PG8_MMA(0, 1, At, B1); PG8_BAR; PG8_SCHED;
;             PG8_LDA(At, 0, 1); PG8_STAGE(PG8_SB(0, 0), b2, voffB); PG8_STAGE(PG8_SB(0, 1), b2 + hstep, voffB); PG8_STAGE(PG8_SA(0, 0), a2, voffA);
;             PG8_WAIT_V(8); PG8_WAIT_L(0); PG8_BAR; PG8_MMA(1, 0, At, B0); PG8_MMA(1, 1, At, B1); PG8_BAR; PG8_SCHED;
;             PG8_LDB(B0, 1, 0); PG8_LDB(B1, 1, 1); PG8_SCHED; PG8_LDA(At, 1, 0); PG8_STAGE(PG8_SA(0, 1), a2 + hstep, voffA);
;             PG8_WAIT_V(8); PG8_WAIT_L(0); PG8_BAR; PG8_MMA(0, 0, At, B0); PG8_MMA(0, 1, At, B1); PG8_BAR; PG8_SCHED;
;             PG8_LDA(At, 1, 1); PG8_STAGE(PG8_SB(1, 0), b3, voffB); PG8_STAGE(PG8_SB(1, 1), b3 + hstep, voffB); PG8_STAGE(PG8_SA(1, 0), a3, voffA);
;     __device__ __forceinline__ void operator()(AccRef acc, const pg8::Unit& u, int wr, int wc, int fr, int fq) const {
;     ...
;             for (int m = 0; m < 4; ++m) {
;                 const int row = row0 + ai * 128 + m * 16;
;                 const float rs = rs_from(ssp + (size_t)row * 16, 4, 1.0f / 1024.0f);
;                 f32x4 o[2];
; #pragma unroll
;                 for (int n = 0; n < 2; ++n)
; #pragma unroll
;                     for (int j = 0; j < 4; ++j) {
;                         const float g = acc[ai][0][m][n][j] * rs, up = acc[ai][1][m][n][j] * rs;
;                         o[n][j] = g * __builtin_amdgcn_rcpf(1.0f + __expf(-g)) * up;
;                     }
;                 *(u32x4*)(act + (size_t)row * FF + col0) = pack8(o[0], o[1]);
	v_mul_f32_e32 v190, v42, v190
	v_mul_f32_e32 v191, v43, v191
	v_cvt_pk_bf16_f32 v196, v184, v185
	v_cvt_pk_bf16_f32 v197, v186, v187
	v_cvt_pk_bf16_f32 v198, v188, v189
	v_cvt_pk_bf16_f32 v199, v190, v191
	v_add_u32_e32 v201, 0xc6000, v248
	global_store_dwordx4 v201, v[196:199], s[48:49]
	v_pk_mul_f32 v[20:21], v[20:21], v[162:163] op_sel_hi:[1,0]
	v_pk_mul_f32 v[22:23], v[22:23], v[162:163] op_sel_hi:[1,0]
	v_pk_mul_f32 v[16:17], v[16:17], v[162:163] op_sel_hi:[1,0]
	v_pk_mul_f32 v[18:19], v[18:19], v[162:163] op_sel_hi:[1,0]
	v_pk_mul_f32 v[28:29], v[28:29], v[162:163] op_sel_hi:[1,0]
	v_pk_mul_f32 v[30:31], v[30:31], v[162:163] op_sel_hi:[1,0]
	v_pk_mul_f32 v[24:25], v[24:25], v[162:163] op_sel_hi:[1,0]
	v_pk_mul_f32 v[26:27], v[26:27], v[162:163] op_sel_hi:[1,0]
	v_mul_f32_e32 v176, 0xbfb8aa3b, v20
	v_mul_f32_e32 v177, 0xbfb8aa3b, v21
	v_mul_f32_e32 v178, 0xbfb8aa3b, v22
	v_mul_f32_e32 v179, 0xbfb8aa3b, v23
	v_mul_f32_e32 v180, 0xbfb8aa3b, v16
	v_mul_f32_e32 v181, 0xbfb8aa3b, v17
	v_mul_f32_e32 v182, 0xbfb8aa3b, v18
	v_mul_f32_e32 v183, 0xbfb8aa3b, v19
	v_exp_f32_e32 v176, v176
	v_exp_f32_e32 v177, v177
	v_exp_f32_e32 v178, v178
	v_exp_f32_e32 v179, v179
	v_exp_f32_e32 v180, v180
	v_exp_f32_e32 v181, v181
	v_exp_f32_e32 v182, v182
	v_exp_f32_e32 v183, v183
	v_add_f32_e32 v176, 1.0, v176
	v_add_f32_e32 v177, 1.0, v177
	v_add_f32_e32 v178, 1.0, v178
	v_add_f32_e32 v179, 1.0, v179
	v_add_f32_e32 v180, 1.0, v180
	v_add_f32_e32 v181, 1.0, v181
	v_add_f32_e32 v182, 1.0, v182
	v_add_f32_e32 v183, 1.0, v183
	v_rcp_f32_e32 v176, v176
	v_rcp_f32_e32 v177, v177
	v_rcp_f32_e32 v178, v178
	v_rcp_f32_e32 v179, v179
	v_rcp_f32_e32 v180, v180
	v_rcp_f32_e32 v181, v181
	v_rcp_f32_e32 v182, v182
	v_rcp_f32_e32 v183, v183
	v_mul_f32_e32 v176, v20, v176
	v_mul_f32_e32 v177, v21, v177
	v_mul_f32_e32 v178, v22, v178
	v_mul_f32_e32 v179, v23, v179
	v_mul_f32_e32 v180, v16, v180
	v_mul_f32_e32 v181, v17, v181
	v_mul_f32_e32 v182, v18, v182
	v_mul_f32_e32 v183, v19, v183
	v_mul_f32_e32 v176, v28, v176
	v_mul_f32_e32 v177, v29, v177
	v_mul_f32_e32 v178, v30, v178
	v_mul_f32_e32 v179, v31, v179
	v_mul_f32_e32 v180, v24, v180
	v_mul_f32_e32 v181, v25, v181
	v_mul_f32_e32 v182, v26, v182
	v_mul_f32_e32 v183, v27, v183
	v_cvt_pk_bf16_f32 v192, v176, v177
	v_cvt_pk_bf16_f32 v193, v178, v179
	v_cvt_pk_bf16_f32 v194, v180, v181
	v_cvt_pk_bf16_f32 v195, v182, v183
	v_add_u32_e32 v200, 0xdc000, v248
	global_store_dwordx4 v200, v[192:195], s[48:49]
	v_pk_mul_f32 v[4:5], v[4:5], v[166:167] op_sel_hi:[1,0]
	v_pk_mul_f32 v[6:7], v[6:7], v[166:167] op_sel_hi:[1,0]
	v_pk_mul_f32 v[0:1], v[0:1], v[166:167] op_sel_hi:[1,0]
	v_pk_mul_f32 v[2:3], v[2:3], v[166:167] op_sel_hi:[1,0]
	v_pk_mul_f32 v[12:13], v[12:13], v[166:167] op_sel_hi:[1,0]
	v_pk_mul_f32 v[14:15], v[14:15], v[166:167] op_sel_hi:[1,0]
	v_pk_mul_f32 v[8:9], v[8:9], v[166:167] op_sel_hi:[1,0]
	v_pk_mul_f32 v[10:11], v[10:11], v[166:167] op_sel_hi:[1,0]
	v_mul_f32_e32 v184, 0xbfb8aa3b, v4
	v_mul_f32_e32 v185, 0xbfb8aa3b, v5
	v_mul_f32_e32 v186, 0xbfb8aa3b, v6
	v_mul_f32_e32 v187, 0xbfb8aa3b, v7
	v_mul_f32_e32 v188, 0xbfb8aa3b, v0
	v_mul_f32_e32 v189, 0xbfb8aa3b, v1
	v_mul_f32_e32 v190, 0xbfb8aa3b, v2
	v_mul_f32_e32 v191, 0xbfb8aa3b, v3
	v_exp_f32_e32 v184, v184
	v_exp_f32_e32 v185, v185
	v_exp_f32_e32 v186, v186
	v_exp_f32_e32 v187, v187
	v_exp_f32_e32 v188, v188
	v_exp_f32_e32 v189, v189
	v_exp_f32_e32 v190, v190
	v_exp_f32_e32 v191, v191
	v_add_f32_e32 v184, 1.0, v184
	v_add_f32_e32 v185, 1.0, v185
	v_add_f32_e32 v186, 1.0, v186
	v_add_f32_e32 v187, 1.0, v187
	v_add_f32_e32 v188, 1.0, v188
	v_add_f32_e32 v189, 1.0, v189
	v_add_f32_e32 v190, 1.0, v190
	v_add_f32_e32 v191, 1.0, v191
	v_rcp_f32_e32 v184, v184
	v_rcp_f32_e32 v185, v185
	v_rcp_f32_e32 v186, v186
	v_rcp_f32_e32 v187, v187
	v_rcp_f32_e32 v188, v188
	v_rcp_f32_e32 v189, v189
	v_rcp_f32_e32 v190, v190
	v_rcp_f32_e32 v191, v191
	v_mul_f32_e32 v184, v4, v184
	v_mul_f32_e32 v185, v5, v185
	v_mul_f32_e32 v186, v6, v186
	v_mul_f32_e32 v187, v7, v187
	v_mul_f32_e32 v188, v0, v188
	v_mul_f32_e32 v189, v1, v189
	v_mul_f32_e32 v190, v2, v190
	v_mul_f32_e32 v191, v3, v191
	v_mul_f32_e32 v184, v12, v184
	v_mul_f32_e32 v185, v13, v185
	v_mul_f32_e32 v186, v14, v186
	v_mul_f32_e32 v187, v15, v187
	v_mul_f32_e32 v188, v8, v188
	v_mul_f32_e32 v189, v9, v189
	v_mul_f32_e32 v190, v10, v190
	v_mul_f32_e32 v191, v11, v191
	v_cvt_pk_bf16_f32 v196, v184, v185
	v_cvt_pk_bf16_f32 v197, v186, v187
	v_cvt_pk_bf16_f32 v198, v188, v189
	v_cvt_pk_bf16_f32 v199, v190, v191
	v_add_u32_e32 v201, 0xf2000, v248
	global_store_dwordx4 v201, v[196:199], s[48:49]
	s_and_b64 vcc, exec, s[2:3]
	s_mov_b64 s[2:3], -1
	s_cbranch_vccnz .LBB0_2472
	s_andn2_b64 vcc, exec, s[12:13]
	s_cbranch_vccnz .LBB0_2471
	s_barrier
	s_branch .LBB0_2471
